# EpiGU ssq loads hoisted to unit start (held in v238-v253 through the K-loop); in-proj layer-0 epilogue de-serialised with double-buffered rope-table loads; removed NaN-canonicalising v_max and 0+x add
# speedup vs baseline: 1.0435x; 1.0023x over previous
; __device__ __forceinline__ u32x4 pack8(f32x4 a, f32x4 b) { u32x4 w; w.x = cvt_pk_bf16(a[0], a[1]); w.y = cvt_pk_bf16(a[2], a[3]); w.z = cvt_pk_bf16(b[0], b[1]); w.w = cvt_pk_bf16(b[2], b[3]); return w; }
;     __device__ __forceinline__ void operator()(const f32x4 (&acc)[2][2][4][2], const Unit& u, int wr, int wc, int fr, int fq) const {
;         const int sec = u.pn >> 1, half = u.pn & 1;
;         bf16_t* dst = qkv + (size_t)sec * M * 512;
;         const float sc = (sec == 0 || sec == 3) ? QSCALE : 1.0f;
;         const bool rp = (sec == 3 || sec == 4);
; #pragma unroll
;         for (int ai = 0; ai < 2; ++ai)
; #pragma unroll
;             for (int m = 0; m < 4; ++m) {
;                 const int row = u.pm * BM + ai * HALF + wr * 64 + m * 16 + fr;
;                 const float rs = __builtin_amdgcn_rsqf(ssq[row] * (1.0f / 1024.0f) + EPS) * sc;
;                 if (rp) {
;                     const int t = row & (T - 1);
;                     const f32x4* rt = (const f32x4*)(rope + ((size_t)t * 32 + 8 * fq) * 2);
;                     f32x4 o1[2], o2[2];
; #pragma unroll
;                     for (int n = 0; n < 2; ++n) {
;                         const f32x4 cs0 = rt[2 * n], cs1 = rt[2 * n + 1];
;                         const f32x4 x1 = acc[ai][0][m][n] * rs, x2 = acc[ai][1][m][n] * rs;
;                         o1[n][0] = x1[0] * cs0[0] - x2[0] * cs0[1]; o2[n][0] = x2[0] * cs0[0] + x1[0] * cs0[1];
;                         o1[n][1] = x1[1] * cs0[2] - x2[1] * cs0[3]; o2[n][1] = x2[1] * cs0[2] + x1[1] * cs0[3];
;                         o1[n][2] = x1[2] * cs1[0] - x2[2] * cs1[1]; o2[n][2] = x2[2] * cs1[0] + x1[2] * cs1[1];
;                         o1[n][3] = x1[3] * cs1[2] - x2[3] * cs1[3]; o2[n][3] = x2[3] * cs1[2] + x1[3] * cs1[3];
;                     }
;                     bf16_t* rowp = dst + (size_t)row * 512 + half * 256 + wc * 64 + 8 * fq;
;                     *(u32x4*)(rowp) = pack8(o1[0], o1[1]);
;                     *(u32x4*)(rowp + 32) = pack8(o2[0], o2[1]);
;                 } else {
;                     bf16_t* rowp = dst + (size_t)row * 512 + half * 256 + wc * 32 + 8 * fq;
; #pragma unroll
;                     for (int bj = 0; bj < 2; ++bj) *(u32x4*)(rowp + bj * HALF) = pack8(acc[ai][bj][m][0] * rs, acc[ai][bj][m][1] * rs);
;                 }
.LBB0_362:
	s_lshl_b32 s2, s6, 8
	v_add_u32_e32 v160, s2, v145
	v_readlane_b32 s56, v254, 0
	v_readlane_b32 s57, v254, 1
	v_lshlrev_b32_e32 v230, 2, v160
	s_nop 4
	global_load_dword v152, v230, s[56:57]
	global_load_dword v154, v230, s[56:57] offset:64
	global_load_dword v156, v230, s[56:57] offset:128
	global_load_dword v158, v230, s[56:57] offset:192
	global_load_dword v170, v230, s[56:57] offset:512
	global_load_dword v172, v230, s[56:57] offset:576
	global_load_dword v174, v230, s[56:57] offset:640
	global_load_dword v176, v230, s[56:57] offset:704
	s_ashr_i32 s26, s22, 1
	s_lshl_b32 s28, s26, 25
	s_lshl_b32 s15, s22, 9
	s_and_b32 s15, s15, 0x200
	s_add_u32 s28, s28, s15
	v_mov_b32_e32 v231, 1.0
	s_cmp_lt_u32 s22, 2
	s_cbranch_scc1 .Lp1_q
	s_cmp_eq_u32 s26, 3
	s_cbranch_scc0 .Lp1_nq
.Lp1_q:
	v_mov_b32_e32 v231, v169
.Lp1_nq:
	v_lshl_add_u32 v232, v160, 10, v138
	s_add_i32 s15, s26, -3
	s_cmp_gt_u32 s15, 1
	s_cbranch_scc0 .Lp1_rope
	s_add_u32 s28, s28, s50
	s_add_u32 s28, s68, s28
	s_addc_u32 s29, s69, 0
	s_waitcnt vmcnt(7)
	v_fmamk_f32 v152, v152, 0x3a800000, v168
	v_rsq_f32_e32 v152, v152
	v_mov_b32_e32 v233, v232
	v_mul_f32_e32 v152, v231, v152
	v_pk_mul_f32 v[124:125], v[124:125], v[152:153] op_sel_hi:[1,0]
	v_pk_mul_f32 v[126:127], v[126:127], v[152:153] op_sel_hi:[1,0]
	v_pk_mul_f32 v[116:117], v[116:117], v[152:153] op_sel_hi:[1,0]
	v_pk_mul_f32 v[118:119], v[118:119], v[152:153] op_sel_hi:[1,0]
	v_pk_mul_f32 v[120:121], v[120:121], v[152:153] op_sel_hi:[1,0]
	v_pk_mul_f32 v[122:123], v[122:123], v[152:153] op_sel_hi:[1,0]
	v_pk_mul_f32 v[112:113], v[112:113], v[152:153] op_sel_hi:[1,0]
	v_pk_mul_f32 v[114:115], v[114:115], v[152:153] op_sel_hi:[1,0]
	v_cvt_pk_bf16_f32 v124, v124, v125
	v_cvt_pk_bf16_f32 v125, v126, v127
	v_cvt_pk_bf16_f32 v126, v116, v117
	v_cvt_pk_bf16_f32 v127, v118, v119
	global_store_dwordx4 v233, v[124:127], s[28:29]
	v_cvt_pk_bf16_f32 v120, v120, v121
	v_cvt_pk_bf16_f32 v121, v122, v123
	v_cvt_pk_bf16_f32 v122, v112, v113
	v_cvt_pk_bf16_f32 v123, v114, v115
	global_store_dwordx4 v233, v[120:123], s[28:29] offset:256
	s_waitcnt vmcnt(8)
	v_fmamk_f32 v154, v154, 0x3a800000, v168
	v_rsq_f32_e32 v154, v154
	v_add_u32_e32 v233, 0x4000, v232
	v_mul_f32_e32 v154, v231, v154
	v_pk_mul_f32 v[108:109], v[108:109], v[154:155] op_sel_hi:[1,0]
	v_pk_mul_f32 v[110:111], v[110:111], v[154:155] op_sel_hi:[1,0]
	v_pk_mul_f32 v[100:101], v[100:101], v[154:155] op_sel_hi:[1,0]
	v_pk_mul_f32 v[102:103], v[102:103], v[154:155] op_sel_hi:[1,0]
	v_pk_mul_f32 v[104:105], v[104:105], v[154:155] op_sel_hi:[1,0]
	v_pk_mul_f32 v[106:107], v[106:107], v[154:155] op_sel_hi:[1,0]
	v_pk_mul_f32 v[96:97], v[96:97], v[154:155] op_sel_hi:[1,0]
	v_pk_mul_f32 v[98:99], v[98:99], v[154:155] op_sel_hi:[1,0]
	v_cvt_pk_bf16_f32 v108, v108, v109
	v_cvt_pk_bf16_f32 v109, v110, v111
	v_cvt_pk_bf16_f32 v110, v100, v101
	v_cvt_pk_bf16_f32 v111, v102, v103
	global_store_dwordx4 v233, v[108:111], s[28:29]
	v_cvt_pk_bf16_f32 v104, v104, v105
	v_cvt_pk_bf16_f32 v105, v106, v107
	v_cvt_pk_bf16_f32 v106, v96, v97
	v_cvt_pk_bf16_f32 v107, v98, v99
	global_store_dwordx4 v233, v[104:107], s[28:29] offset:256
	s_waitcnt vmcnt(9)
	v_fmamk_f32 v156, v156, 0x3a800000, v168
	v_rsq_f32_e32 v156, v156
	v_add_u32_e32 v233, 0x8000, v232
	v_mul_f32_e32 v156, v231, v156
	v_pk_mul_f32 v[92:93], v[92:93], v[156:157] op_sel_hi:[1,0]
	v_pk_mul_f32 v[94:95], v[94:95], v[156:157] op_sel_hi:[1,0]
	v_pk_mul_f32 v[84:85], v[84:85], v[156:157] op_sel_hi:[1,0]
	v_pk_mul_f32 v[86:87], v[86:87], v[156:157] op_sel_hi:[1,0]
	v_pk_mul_f32 v[88:89], v[88:89], v[156:157] op_sel_hi:[1,0]
	v_pk_mul_f32 v[90:91], v[90:91], v[156:157] op_sel_hi:[1,0]
	v_pk_mul_f32 v[80:81], v[80:81], v[156:157] op_sel_hi:[1,0]
	v_pk_mul_f32 v[82:83], v[82:83], v[156:157] op_sel_hi:[1,0]
	v_cvt_pk_bf16_f32 v92, v92, v93
	v_cvt_pk_bf16_f32 v93, v94, v95
	v_cvt_pk_bf16_f32 v94, v84, v85
	v_cvt_pk_bf16_f32 v95, v86, v87
	global_store_dwordx4 v233, v[92:95], s[28:29]
	v_cvt_pk_bf16_f32 v88, v88, v89
	v_cvt_pk_bf16_f32 v89, v90, v91
	v_cvt_pk_bf16_f32 v90, v80, v81
	v_cvt_pk_bf16_f32 v91, v82, v83
	global_store_dwordx4 v233, v[88:91], s[28:29] offset:256
	s_waitcnt vmcnt(10)
	v_fmamk_f32 v158, v158, 0x3a800000, v168
	v_rsq_f32_e32 v158, v158
	v_add_u32_e32 v233, 0xc000, v232
	v_mul_f32_e32 v158, v231, v158
	v_pk_mul_f32 v[76:77], v[76:77], v[158:159] op_sel_hi:[1,0]
	v_pk_mul_f32 v[78:79], v[78:79], v[158:159] op_sel_hi:[1,0]
	v_pk_mul_f32 v[68:69], v[68:69], v[158:159] op_sel_hi:[1,0]
	v_pk_mul_f32 v[70:71], v[70:71], v[158:159] op_sel_hi:[1,0]
	v_pk_mul_f32 v[72:73], v[72:73], v[158:159] op_sel_hi:[1,0]
	v_pk_mul_f32 v[74:75], v[74:75], v[158:159] op_sel_hi:[1,0]
	v_pk_mul_f32 v[64:65], v[64:65], v[158:159] op_sel_hi:[1,0]
	v_pk_mul_f32 v[66:67], v[66:67], v[158:159] op_sel_hi:[1,0]
	v_cvt_pk_bf16_f32 v76, v76, v77
	v_cvt_pk_bf16_f32 v77, v78, v79
	v_cvt_pk_bf16_f32 v78, v68, v69
	v_cvt_pk_bf16_f32 v79, v70, v71
	global_store_dwordx4 v233, v[76:79], s[28:29]
	v_cvt_pk_bf16_f32 v72, v72, v73
	v_cvt_pk_bf16_f32 v73, v74, v75
	v_cvt_pk_bf16_f32 v74, v64, v65
	v_cvt_pk_bf16_f32 v75, v66, v67
	global_store_dwordx4 v233, v[72:75], s[28:29] offset:256
	s_waitcnt vmcnt(11)
; __device__ __forceinline__ u32x4 pack8(f32x4 a, f32x4 b) { u32x4 w; w.x = cvt_pk_bf16(a[0], a[1]); w.y = cvt_pk_bf16(a[2], a[3]); w.z = cvt_pk_bf16(b[0], b[1]); w.w = cvt_pk_bf16(b[2], b[3]); return w; }
; __device__ __forceinline__ bf16x8 pack8(const f32x16& p, int b) { u32x4 w; w.x = cvtpk(p[b], p[b + 1]); w.y = cvtpk(p[b + 2], p[b + 3]); w.z = cvtpk(p[b + 4], p[b + 5]); w.w = cvtpk(p[b + 6], p[b + 7]); return __builtin_bit_cast(bf16x8, w); }
;     __device__ __forceinline__ void operator()(const f32x4 (&acc)[2][2][4][2], const Unit& u, int wr, int wc, int fr, int fq) const {
;     ...
;             for (int m = 0; m < 4; ++m) {
;                 const int row = u.pm * BM + ai * HALF + wr * 64 + m * 16 + fr;
;                 const float rs = __builtin_amdgcn_rsqf(ssq[row] * (1.0f / 1024.0f) + EPS) * sc;
;                 if (rp) {
;                     const int t = row & (T - 1);
;                     const f32x4* rt = (const f32x4*)(rope + ((size_t)t * 32 + 8 * fq) * 2);
;                     f32x4 o1[2], o2[2];
; #pragma unroll
;                     for (int n = 0; n < 2; ++n) {
;                         const f32x4 cs0 = rt[2 * n], cs1 = rt[2 * n + 1];
;                         const f32x4 x1 = acc[ai][0][m][n] * rs, x2 = acc[ai][1][m][n] * rs;
;                         o1[n][0] = x1[0] * cs0[0] - x2[0] * cs0[1]; o2[n][0] = x2[0] * cs0[0] + x1[0] * cs0[1];
;                         o1[n][1] = x1[1] * cs0[2] - x2[1] * cs0[3]; o2[n][1] = x2[1] * cs0[2] + x1[1] * cs0[3];
;                         o1[n][2] = x1[2] * cs1[0] - x2[2] * cs1[1]; o2[n][2] = x2[2] * cs1[0] + x1[2] * cs1[1];
;                         o1[n][3] = x1[3] * cs1[2] - x2[3] * cs1[3]; o2[n][3] = x2[3] * cs1[2] + x1[3] * cs1[3];
;                     }
;                     bf16_t* rowp = dst + (size_t)row * 512 + half * 256 + wc * 64 + 8 * fq;
;                     *(u32x4*)(rowp) = pack8(o1[0], o1[1]);
;                     *(u32x4*)(rowp + 32) = pack8(o2[0], o2[1]);
;                 } else {
;                     bf16_t* rowp = dst + (size_t)row * 512 + half * 256 + wc * 32 + 8 * fq;
; #pragma unroll
;                     for (int bj = 0; bj < 2; ++bj) *(u32x4*)(rowp + bj * HALF) = pack8(acc[ai][bj][m][0] * rs, acc[ai][bj][m][1] * rs);
;                 }
	v_fmamk_f32 v170, v170, 0x3a800000, v168
	v_rsq_f32_e32 v170, v170
	v_add_u32_e32 v233, 0x20000, v232
	v_mul_f32_e32 v170, v231, v170
	v_pk_mul_f32 v[60:61], v[60:61], v[170:171] op_sel_hi:[1,0]
	v_pk_mul_f32 v[62:63], v[62:63], v[170:171] op_sel_hi:[1,0]
	v_pk_mul_f32 v[52:53], v[52:53], v[170:171] op_sel_hi:[1,0]
	v_pk_mul_f32 v[54:55], v[54:55], v[170:171] op_sel_hi:[1,0]
	v_pk_mul_f32 v[56:57], v[56:57], v[170:171] op_sel_hi:[1,0]
	v_pk_mul_f32 v[58:59], v[58:59], v[170:171] op_sel_hi:[1,0]
	v_pk_mul_f32 v[48:49], v[48:49], v[170:171] op_sel_hi:[1,0]
	v_pk_mul_f32 v[50:51], v[50:51], v[170:171] op_sel_hi:[1,0]
	v_cvt_pk_bf16_f32 v60, v60, v61
	v_cvt_pk_bf16_f32 v61, v62, v63
	v_cvt_pk_bf16_f32 v62, v52, v53
	v_cvt_pk_bf16_f32 v63, v54, v55
	global_store_dwordx4 v233, v[60:63], s[28:29]
	v_cvt_pk_bf16_f32 v56, v56, v57
	v_cvt_pk_bf16_f32 v57, v58, v59
	v_cvt_pk_bf16_f32 v58, v48, v49
	v_cvt_pk_bf16_f32 v59, v50, v51
	global_store_dwordx4 v233, v[56:59], s[28:29] offset:256
	s_waitcnt vmcnt(12)
	v_fmamk_f32 v172, v172, 0x3a800000, v168
	v_rsq_f32_e32 v172, v172
	v_add_u32_e32 v233, 0x24000, v232
	v_mul_f32_e32 v172, v231, v172
	v_pk_mul_f32 v[44:45], v[44:45], v[172:173] op_sel_hi:[1,0]
	v_pk_mul_f32 v[46:47], v[46:47], v[172:173] op_sel_hi:[1,0]
	v_pk_mul_f32 v[36:37], v[36:37], v[172:173] op_sel_hi:[1,0]
	v_pk_mul_f32 v[38:39], v[38:39], v[172:173] op_sel_hi:[1,0]
	v_pk_mul_f32 v[40:41], v[40:41], v[172:173] op_sel_hi:[1,0]
	v_pk_mul_f32 v[42:43], v[42:43], v[172:173] op_sel_hi:[1,0]
	v_pk_mul_f32 v[32:33], v[32:33], v[172:173] op_sel_hi:[1,0]
	v_pk_mul_f32 v[34:35], v[34:35], v[172:173] op_sel_hi:[1,0]
	v_cvt_pk_bf16_f32 v44, v44, v45
	v_cvt_pk_bf16_f32 v45, v46, v47
	v_cvt_pk_bf16_f32 v46, v36, v37
	v_cvt_pk_bf16_f32 v47, v38, v39
	global_store_dwordx4 v233, v[44:47], s[28:29]
	v_cvt_pk_bf16_f32 v40, v40, v41
	v_cvt_pk_bf16_f32 v41, v42, v43
	v_cvt_pk_bf16_f32 v42, v32, v33
	v_cvt_pk_bf16_f32 v43, v34, v35
	global_store_dwordx4 v233, v[40:43], s[28:29] offset:256
	s_waitcnt vmcnt(13)
	v_fmamk_f32 v174, v174, 0x3a800000, v168
	v_rsq_f32_e32 v174, v174
	v_add_u32_e32 v233, 0x28000, v232
	v_mul_f32_e32 v174, v231, v174
	v_pk_mul_f32 v[28:29], v[28:29], v[174:175] op_sel_hi:[1,0]
	v_pk_mul_f32 v[30:31], v[30:31], v[174:175] op_sel_hi:[1,0]
	v_pk_mul_f32 v[20:21], v[20:21], v[174:175] op_sel_hi:[1,0]
	v_pk_mul_f32 v[22:23], v[22:23], v[174:175] op_sel_hi:[1,0]
	v_pk_mul_f32 v[24:25], v[24:25], v[174:175] op_sel_hi:[1,0]
	v_pk_mul_f32 v[26:27], v[26:27], v[174:175] op_sel_hi:[1,0]
	v_pk_mul_f32 v[16:17], v[16:17], v[174:175] op_sel_hi:[1,0]
	v_pk_mul_f32 v[18:19], v[18:19], v[174:175] op_sel_hi:[1,0]
	v_cvt_pk_bf16_f32 v28, v28, v29
	v_cvt_pk_bf16_f32 v29, v30, v31
	v_cvt_pk_bf16_f32 v30, v20, v21
	v_cvt_pk_bf16_f32 v31, v22, v23
	global_store_dwordx4 v233, v[28:31], s[28:29]
	v_cvt_pk_bf16_f32 v24, v24, v25
	v_cvt_pk_bf16_f32 v25, v26, v27
	v_cvt_pk_bf16_f32 v26, v16, v17
	v_cvt_pk_bf16_f32 v27, v18, v19
	global_store_dwordx4 v233, v[24:27], s[28:29] offset:256
	s_waitcnt vmcnt(14)
	v_fmamk_f32 v176, v176, 0x3a800000, v168
	v_rsq_f32_e32 v176, v176
	v_add_u32_e32 v233, 0x2c000, v232
	v_mul_f32_e32 v176, v231, v176
	v_pk_mul_f32 v[12:13], v[12:13], v[176:177] op_sel_hi:[1,0]
	v_pk_mul_f32 v[14:15], v[14:15], v[176:177] op_sel_hi:[1,0]
	v_pk_mul_f32 v[4:5], v[4:5], v[176:177] op_sel_hi:[1,0]
	v_pk_mul_f32 v[6:7], v[6:7], v[176:177] op_sel_hi:[1,0]
	v_pk_mul_f32 v[8:9], v[8:9], v[176:177] op_sel_hi:[1,0]
	v_pk_mul_f32 v[10:11], v[10:11], v[176:177] op_sel_hi:[1,0]
	v_pk_mul_f32 v[0:1], v[0:1], v[176:177] op_sel_hi:[1,0]
	v_pk_mul_f32 v[2:3], v[2:3], v[176:177] op_sel_hi:[1,0]
	v_cvt_pk_bf16_f32 v12, v12, v13
	v_cvt_pk_bf16_f32 v13, v14, v15
	v_cvt_pk_bf16_f32 v14, v4, v5
	v_cvt_pk_bf16_f32 v15, v6, v7
	global_store_dwordx4 v233, v[12:15], s[28:29]
	v_cvt_pk_bf16_f32 v8, v8, v9
	v_cvt_pk_bf16_f32 v9, v10, v11
	v_cvt_pk_bf16_f32 v10, v0, v1
	v_cvt_pk_bf16_f32 v11, v2, v3
	global_store_dwordx4 v233, v[8:11], s[28:29] offset:256
	s_branch .Lp1_done
.Lp1_rope:
	s_add_u32 s28, s28, s51
	s_add_u32 s28, s68, s28
	s_addc_u32 s29, s69, 0
	v_lshlrev_b32_e32 v230, 8, v160
	v_and_b32_e32 v230, 0x3fff00, v230
	v_lshl_or_b32 v230, v140, 3, v230
	v_mov_b32_e32 v160, v230
	global_load_dwordx4 v[178:181], v160, s[20:21]
	global_load_dwordx4 v[182:185], v160, s[20:21] offset:16
	global_load_dwordx4 v[186:189], v160, s[20:21] offset:32
	global_load_dwordx4 v[190:193], v160, s[20:21] offset:48
	v_add_u32_e32 v160, 0x1000, v230
	global_load_dwordx4 v[214:217], v160, s[20:21]
	global_load_dwordx4 v[218:221], v160, s[20:21] offset:16
	global_load_dwordx4 v[222:225], v160, s[20:21] offset:32
	global_load_dwordx4 v[226:229], v160, s[20:21] offset:48
	s_waitcnt vmcnt(4)
; __device__ __forceinline__ u32x4 pack8(f32x4 a, f32x4 b) { u32x4 w; w.x = cvt_pk_bf16(a[0], a[1]); w.y = cvt_pk_bf16(a[2], a[3]); w.z = cvt_pk_bf16(b[0], b[1]); w.w = cvt_pk_bf16(b[2], b[3]); return w; }
; __device__ __forceinline__ bf16x8 pack8(const f32x16& p, int b) { u32x4 w; w.x = cvtpk(p[b], p[b + 1]); w.y = cvtpk(p[b + 2], p[b + 3]); w.z = cvtpk(p[b + 4], p[b + 5]); w.w = cvtpk(p[b + 6], p[b + 7]); return __builtin_bit_cast(bf16x8, w); }
;     __device__ __forceinline__ void operator()(const f32x4 (&acc)[2][2][4][2], const Unit& u, int wr, int wc, int fr, int fq) const {
;     ...
;                 if (rp) {
;                     const int t = row & (T - 1);
;                     const f32x4* rt = (const f32x4*)(rope + ((size_t)t * 32 + 8 * fq) * 2);
;                     f32x4 o1[2], o2[2];
; #pragma unroll
;                     for (int n = 0; n < 2; ++n) {
;                         const f32x4 cs0 = rt[2 * n], cs1 = rt[2 * n + 1];
;                         const f32x4 x1 = acc[ai][0][m][n] * rs, x2 = acc[ai][1][m][n] * rs;
;                         o1[n][0] = x1[0] * cs0[0] - x2[0] * cs0[1]; o2[n][0] = x2[0] * cs0[0] + x1[0] * cs0[1];
;                         o1[n][1] = x1[1] * cs0[2] - x2[1] * cs0[3]; o2[n][1] = x2[1] * cs0[2] + x1[1] * cs0[3];
;                         o1[n][2] = x1[2] * cs1[0] - x2[2] * cs1[1]; o2[n][2] = x2[2] * cs1[0] + x1[2] * cs1[1];
;                         o1[n][3] = x1[3] * cs1[2] - x2[3] * cs1[3]; o2[n][3] = x2[3] * cs1[2] + x1[3] * cs1[3];
;                     }
;                     bf16_t* rowp = dst + (size_t)row * 512 + half * 256 + wc * 64 + 8 * fq;
;                     *(u32x4*)(rowp) = pack8(o1[0], o1[1]);
;                     *(u32x4*)(rowp + 32) = pack8(o2[0], o2[1]);
	v_fmamk_f32 v152, v152, 0x3a800000, v168
	v_rsq_f32_e32 v152, v152
	v_mov_b32_e32 v233, v232
	v_mul_f32_e32 v152, v231, v152
	v_pk_mul_f32 v[124:125], v[124:125], v[152:153] op_sel_hi:[1,0]
	v_pk_mul_f32 v[126:127], v[126:127], v[152:153] op_sel_hi:[1,0]
	v_pk_mul_f32 v[116:117], v[116:117], v[152:153] op_sel_hi:[1,0]
	v_pk_mul_f32 v[118:119], v[118:119], v[152:153] op_sel_hi:[1,0]
	v_pk_mul_f32 v[120:121], v[120:121], v[152:153] op_sel_hi:[1,0]
	v_pk_mul_f32 v[122:123], v[122:123], v[152:153] op_sel_hi:[1,0]
	v_pk_mul_f32 v[112:113], v[112:113], v[152:153] op_sel_hi:[1,0]
	v_pk_mul_f32 v[114:115], v[114:115], v[152:153] op_sel_hi:[1,0]
	v_mul_f32_e32 v194, v124, v178
	v_mul_f32_e32 v195, v120, v179
	v_mul_f32_e32 v196, v120, v178
	v_mul_f32_e32 v197, v124, v179
	v_sub_f32_e32 v124, v194, v195
	v_add_f32_e32 v120, v196, v197
	v_mul_f32_e32 v194, v125, v180
	v_mul_f32_e32 v195, v121, v181
	v_mul_f32_e32 v196, v121, v180
	v_mul_f32_e32 v197, v125, v181
	v_sub_f32_e32 v125, v194, v195
	v_add_f32_e32 v121, v196, v197
	v_mul_f32_e32 v194, v126, v182
	v_mul_f32_e32 v195, v122, v183
	v_mul_f32_e32 v196, v122, v182
	v_mul_f32_e32 v197, v126, v183
	v_sub_f32_e32 v126, v194, v195
	v_add_f32_e32 v122, v196, v197
	v_mul_f32_e32 v194, v127, v184
	v_mul_f32_e32 v195, v123, v185
	v_mul_f32_e32 v196, v123, v184
	v_mul_f32_e32 v197, v127, v185
	v_sub_f32_e32 v127, v194, v195
	v_add_f32_e32 v123, v196, v197
	v_mul_f32_e32 v194, v116, v186
	v_mul_f32_e32 v195, v112, v187
	v_mul_f32_e32 v196, v112, v186
	v_mul_f32_e32 v197, v116, v187
	v_sub_f32_e32 v116, v194, v195
	v_add_f32_e32 v112, v196, v197
	v_mul_f32_e32 v194, v117, v188
	v_mul_f32_e32 v195, v113, v189
	v_mul_f32_e32 v196, v113, v188
	v_mul_f32_e32 v197, v117, v189
	v_sub_f32_e32 v117, v194, v195
	v_add_f32_e32 v113, v196, v197
	v_mul_f32_e32 v194, v118, v190
	v_mul_f32_e32 v195, v114, v191
	v_mul_f32_e32 v196, v114, v190
	v_mul_f32_e32 v197, v118, v191
	v_sub_f32_e32 v118, v194, v195
	v_add_f32_e32 v114, v196, v197
	v_mul_f32_e32 v194, v119, v192
	v_mul_f32_e32 v195, v115, v193
	v_mul_f32_e32 v196, v115, v192
	v_mul_f32_e32 v197, v119, v193
	v_sub_f32_e32 v119, v194, v195
	v_add_f32_e32 v115, v196, v197
	v_add_u32_e32 v160, 0x2000, v230
	global_load_dwordx4 v[178:181], v160, s[20:21]
	global_load_dwordx4 v[182:185], v160, s[20:21] offset:16
	global_load_dwordx4 v[186:189], v160, s[20:21] offset:32
	global_load_dwordx4 v[190:193], v160, s[20:21] offset:48
	v_cvt_pk_bf16_f32 v124, v124, v125
	v_cvt_pk_bf16_f32 v125, v126, v127
	v_cvt_pk_bf16_f32 v126, v116, v117
	v_cvt_pk_bf16_f32 v127, v118, v119
	global_store_dwordx4 v233, v[124:127], s[28:29]
	v_cvt_pk_bf16_f32 v120, v120, v121
	v_cvt_pk_bf16_f32 v121, v122, v123
	v_cvt_pk_bf16_f32 v122, v112, v113
	v_cvt_pk_bf16_f32 v123, v114, v115
	global_store_dwordx4 v233, v[120:123], s[28:29] offset:64
	s_waitcnt vmcnt(6)
	v_fmamk_f32 v154, v154, 0x3a800000, v168
	v_rsq_f32_e32 v154, v154
	v_add_u32_e32 v233, 0x4000, v232
	v_mul_f32_e32 v154, v231, v154
	v_pk_mul_f32 v[108:109], v[108:109], v[154:155] op_sel_hi:[1,0]
	v_pk_mul_f32 v[110:111], v[110:111], v[154:155] op_sel_hi:[1,0]
	v_pk_mul_f32 v[100:101], v[100:101], v[154:155] op_sel_hi:[1,0]
	v_pk_mul_f32 v[102:103], v[102:103], v[154:155] op_sel_hi:[1,0]
	v_pk_mul_f32 v[104:105], v[104:105], v[154:155] op_sel_hi:[1,0]
	v_pk_mul_f32 v[106:107], v[106:107], v[154:155] op_sel_hi:[1,0]
	v_pk_mul_f32 v[96:97], v[96:97], v[154:155] op_sel_hi:[1,0]
	v_pk_mul_f32 v[98:99], v[98:99], v[154:155] op_sel_hi:[1,0]
	v_mul_f32_e32 v194, v108, v214
	v_mul_f32_e32 v195, v104, v215
	v_mul_f32_e32 v196, v104, v214
	v_mul_f32_e32 v197, v108, v215
	v_sub_f32_e32 v108, v194, v195
	v_add_f32_e32 v104, v196, v197
	v_mul_f32_e32 v194, v109, v216
	v_mul_f32_e32 v195, v105, v217
	v_mul_f32_e32 v196, v105, v216
	v_mul_f32_e32 v197, v109, v217
	v_sub_f32_e32 v109, v194, v195
	v_add_f32_e32 v105, v196, v197
	v_mul_f32_e32 v194, v110, v218
	v_mul_f32_e32 v195, v106, v219
	v_mul_f32_e32 v196, v106, v218
	v_mul_f32_e32 v197, v110, v219
	v_sub_f32_e32 v110, v194, v195
	v_add_f32_e32 v106, v196, v197
	v_mul_f32_e32 v194, v111, v220
	v_mul_f32_e32 v195, v107, v221
	v_mul_f32_e32 v196, v107, v220
	v_mul_f32_e32 v197, v111, v221
	v_sub_f32_e32 v111, v194, v195
	v_add_f32_e32 v107, v196, v197
	v_mul_f32_e32 v194, v100, v222
	v_mul_f32_e32 v195, v96, v223
	v_mul_f32_e32 v196, v96, v222
	v_mul_f32_e32 v197, v100, v223
	v_sub_f32_e32 v100, v194, v195
	v_add_f32_e32 v96, v196, v197
	v_mul_f32_e32 v194, v101, v224
	v_mul_f32_e32 v195, v97, v225
	v_mul_f32_e32 v196, v97, v224
	v_mul_f32_e32 v197, v101, v225
	v_sub_f32_e32 v101, v194, v195
	v_add_f32_e32 v97, v196, v197
	v_mul_f32_e32 v194, v102, v226
	v_mul_f32_e32 v195, v98, v227
	v_mul_f32_e32 v196, v98, v226
	v_mul_f32_e32 v197, v102, v227
	v_sub_f32_e32 v102, v194, v195
	v_add_f32_e32 v98, v196, v197
	v_mul_f32_e32 v194, v103, v228
	v_mul_f32_e32 v195, v99, v229
	v_mul_f32_e32 v196, v99, v228
	v_mul_f32_e32 v197, v103, v229
	v_sub_f32_e32 v103, v194, v195
	v_add_f32_e32 v99, v196, v197
	v_add_u32_e32 v160, 0x3000, v230
	global_load_dwordx4 v[214:217], v160, s[20:21]
	global_load_dwordx4 v[218:221], v160, s[20:21] offset:16
	global_load_dwordx4 v[222:225], v160, s[20:21] offset:32
	global_load_dwordx4 v[226:229], v160, s[20:21] offset:48
	v_cvt_pk_bf16_f32 v108, v108, v109
	v_cvt_pk_bf16_f32 v109, v110, v111
	v_cvt_pk_bf16_f32 v110, v100, v101
	v_cvt_pk_bf16_f32 v111, v102, v103
	global_store_dwordx4 v233, v[108:111], s[28:29]
	v_cvt_pk_bf16_f32 v104, v104, v105
	v_cvt_pk_bf16_f32 v105, v106, v107
	v_cvt_pk_bf16_f32 v106, v96, v97
	v_cvt_pk_bf16_f32 v107, v98, v99
	global_store_dwordx4 v233, v[104:107], s[28:29] offset:64
	s_waitcnt vmcnt(8)
; __device__ __forceinline__ u32x4 pack8(f32x4 a, f32x4 b) { u32x4 w; w.x = cvt_pk_bf16(a[0], a[1]); w.y = cvt_pk_bf16(a[2], a[3]); w.z = cvt_pk_bf16(b[0], b[1]); w.w = cvt_pk_bf16(b[2], b[3]); return w; }
; __device__ __forceinline__ bf16x8 pack8(const f32x16& p, int b) { u32x4 w; w.x = cvtpk(p[b], p[b + 1]); w.y = cvtpk(p[b + 2], p[b + 3]); w.z = cvtpk(p[b + 4], p[b + 5]); w.w = cvtpk(p[b + 6], p[b + 7]); return __builtin_bit_cast(bf16x8, w); }
;     __device__ __forceinline__ void operator()(const f32x4 (&acc)[2][2][4][2], const Unit& u, int wr, int wc, int fr, int fq) const {
;     ...
;                 if (rp) {
;                     const int t = row & (T - 1);
;                     const f32x4* rt = (const f32x4*)(rope + ((size_t)t * 32 + 8 * fq) * 2);
;                     f32x4 o1[2], o2[2];
; #pragma unroll
;                     for (int n = 0; n < 2; ++n) {
;                         const f32x4 cs0 = rt[2 * n], cs1 = rt[2 * n + 1];
;                         const f32x4 x1 = acc[ai][0][m][n] * rs, x2 = acc[ai][1][m][n] * rs;
;                         o1[n][0] = x1[0] * cs0[0] - x2[0] * cs0[1]; o2[n][0] = x2[0] * cs0[0] + x1[0] * cs0[1];
;                         o1[n][1] = x1[1] * cs0[2] - x2[1] * cs0[3]; o2[n][1] = x2[1] * cs0[2] + x1[1] * cs0[3];
;                         o1[n][2] = x1[2] * cs1[0] - x2[2] * cs1[1]; o2[n][2] = x2[2] * cs1[0] + x1[2] * cs1[1];
;                         o1[n][3] = x1[3] * cs1[2] - x2[3] * cs1[3]; o2[n][3] = x2[3] * cs1[2] + x1[3] * cs1[3];
;                     }
;                     bf16_t* rowp = dst + (size_t)row * 512 + half * 256 + wc * 64 + 8 * fq;
;                     *(u32x4*)(rowp) = pack8(o1[0], o1[1]);
;                     *(u32x4*)(rowp + 32) = pack8(o2[0], o2[1]);
	v_fmamk_f32 v156, v156, 0x3a800000, v168
	v_rsq_f32_e32 v156, v156
	v_add_u32_e32 v233, 0x8000, v232
	v_mul_f32_e32 v156, v231, v156
	v_pk_mul_f32 v[92:93], v[92:93], v[156:157] op_sel_hi:[1,0]
	v_pk_mul_f32 v[94:95], v[94:95], v[156:157] op_sel_hi:[1,0]
	v_pk_mul_f32 v[84:85], v[84:85], v[156:157] op_sel_hi:[1,0]
	v_pk_mul_f32 v[86:87], v[86:87], v[156:157] op_sel_hi:[1,0]
	v_pk_mul_f32 v[88:89], v[88:89], v[156:157] op_sel_hi:[1,0]
	v_pk_mul_f32 v[90:91], v[90:91], v[156:157] op_sel_hi:[1,0]
	v_pk_mul_f32 v[80:81], v[80:81], v[156:157] op_sel_hi:[1,0]
	v_pk_mul_f32 v[82:83], v[82:83], v[156:157] op_sel_hi:[1,0]
	v_mul_f32_e32 v194, v92, v178
	v_mul_f32_e32 v195, v88, v179
	v_mul_f32_e32 v196, v88, v178
	v_mul_f32_e32 v197, v92, v179
	v_sub_f32_e32 v92, v194, v195
	v_add_f32_e32 v88, v196, v197
	v_mul_f32_e32 v194, v93, v180
	v_mul_f32_e32 v195, v89, v181
	v_mul_f32_e32 v196, v89, v180
	v_mul_f32_e32 v197, v93, v181
	v_sub_f32_e32 v93, v194, v195
	v_add_f32_e32 v89, v196, v197
	v_mul_f32_e32 v194, v94, v182
	v_mul_f32_e32 v195, v90, v183
	v_mul_f32_e32 v196, v90, v182
	v_mul_f32_e32 v197, v94, v183
	v_sub_f32_e32 v94, v194, v195
	v_add_f32_e32 v90, v196, v197
	v_mul_f32_e32 v194, v95, v184
	v_mul_f32_e32 v195, v91, v185
	v_mul_f32_e32 v196, v91, v184
	v_mul_f32_e32 v197, v95, v185
	v_sub_f32_e32 v95, v194, v195
	v_add_f32_e32 v91, v196, v197
	v_mul_f32_e32 v194, v84, v186
	v_mul_f32_e32 v195, v80, v187
	v_mul_f32_e32 v196, v80, v186
	v_mul_f32_e32 v197, v84, v187
	v_sub_f32_e32 v84, v194, v195
	v_add_f32_e32 v80, v196, v197
	v_mul_f32_e32 v194, v85, v188
	v_mul_f32_e32 v195, v81, v189
	v_mul_f32_e32 v196, v81, v188
	v_mul_f32_e32 v197, v85, v189
	v_sub_f32_e32 v85, v194, v195
	v_add_f32_e32 v81, v196, v197
	v_mul_f32_e32 v194, v86, v190
	v_mul_f32_e32 v195, v82, v191
	v_mul_f32_e32 v196, v82, v190
	v_mul_f32_e32 v197, v86, v191
	v_sub_f32_e32 v86, v194, v195
	v_add_f32_e32 v82, v196, v197
	v_mul_f32_e32 v194, v87, v192
	v_mul_f32_e32 v195, v83, v193
	v_mul_f32_e32 v196, v83, v192
	v_mul_f32_e32 v197, v87, v193
	v_sub_f32_e32 v87, v194, v195
	v_add_f32_e32 v83, v196, v197
	v_add_u32_e32 v160, 0x8000, v230
	global_load_dwordx4 v[178:181], v160, s[20:21]
	global_load_dwordx4 v[182:185], v160, s[20:21] offset:16
	global_load_dwordx4 v[186:189], v160, s[20:21] offset:32
	global_load_dwordx4 v[190:193], v160, s[20:21] offset:48
	v_cvt_pk_bf16_f32 v92, v92, v93
	v_cvt_pk_bf16_f32 v93, v94, v95
	v_cvt_pk_bf16_f32 v94, v84, v85
	v_cvt_pk_bf16_f32 v95, v86, v87
	global_store_dwordx4 v233, v[92:95], s[28:29]
	v_cvt_pk_bf16_f32 v88, v88, v89
	v_cvt_pk_bf16_f32 v89, v90, v91
	v_cvt_pk_bf16_f32 v90, v80, v81
	v_cvt_pk_bf16_f32 v91, v82, v83
	global_store_dwordx4 v233, v[88:91], s[28:29] offset:64
	s_waitcnt vmcnt(8)
	v_fmamk_f32 v158, v158, 0x3a800000, v168
	v_rsq_f32_e32 v158, v158
	v_add_u32_e32 v233, 0xc000, v232
	v_mul_f32_e32 v158, v231, v158
	v_pk_mul_f32 v[76:77], v[76:77], v[158:159] op_sel_hi:[1,0]
	v_pk_mul_f32 v[78:79], v[78:79], v[158:159] op_sel_hi:[1,0]
	v_pk_mul_f32 v[68:69], v[68:69], v[158:159] op_sel_hi:[1,0]
	v_pk_mul_f32 v[70:71], v[70:71], v[158:159] op_sel_hi:[1,0]
	v_pk_mul_f32 v[72:73], v[72:73], v[158:159] op_sel_hi:[1,0]
	v_pk_mul_f32 v[74:75], v[74:75], v[158:159] op_sel_hi:[1,0]
	v_pk_mul_f32 v[64:65], v[64:65], v[158:159] op_sel_hi:[1,0]
	v_pk_mul_f32 v[66:67], v[66:67], v[158:159] op_sel_hi:[1,0]
	v_mul_f32_e32 v194, v76, v214
	v_mul_f32_e32 v195, v72, v215
	v_mul_f32_e32 v196, v72, v214
	v_mul_f32_e32 v197, v76, v215
	v_sub_f32_e32 v76, v194, v195
	v_add_f32_e32 v72, v196, v197
	v_mul_f32_e32 v194, v77, v216
	v_mul_f32_e32 v195, v73, v217
	v_mul_f32_e32 v196, v73, v216
	v_mul_f32_e32 v197, v77, v217
	v_sub_f32_e32 v77, v194, v195
	v_add_f32_e32 v73, v196, v197
	v_mul_f32_e32 v194, v78, v218
	v_mul_f32_e32 v195, v74, v219
	v_mul_f32_e32 v196, v74, v218
	v_mul_f32_e32 v197, v78, v219
	v_sub_f32_e32 v78, v194, v195
	v_add_f32_e32 v74, v196, v197
	v_mul_f32_e32 v194, v79, v220
	v_mul_f32_e32 v195, v75, v221
	v_mul_f32_e32 v196, v75, v220
	v_mul_f32_e32 v197, v79, v221
	v_sub_f32_e32 v79, v194, v195
	v_add_f32_e32 v75, v196, v197
	v_mul_f32_e32 v194, v68, v222
	v_mul_f32_e32 v195, v64, v223
	v_mul_f32_e32 v196, v64, v222
	v_mul_f32_e32 v197, v68, v223
	v_sub_f32_e32 v68, v194, v195
	v_add_f32_e32 v64, v196, v197
	v_mul_f32_e32 v194, v69, v224
	v_mul_f32_e32 v195, v65, v225
	v_mul_f32_e32 v196, v65, v224
	v_mul_f32_e32 v197, v69, v225
	v_sub_f32_e32 v69, v194, v195
	v_add_f32_e32 v65, v196, v197
	v_mul_f32_e32 v194, v70, v226
	v_mul_f32_e32 v195, v66, v227
	v_mul_f32_e32 v196, v66, v226
	v_mul_f32_e32 v197, v70, v227
	v_sub_f32_e32 v70, v194, v195
	v_add_f32_e32 v66, v196, v197
	v_mul_f32_e32 v194, v71, v228
	v_mul_f32_e32 v195, v67, v229
	v_mul_f32_e32 v196, v67, v228
	v_mul_f32_e32 v197, v71, v229
	v_sub_f32_e32 v71, v194, v195
	v_add_f32_e32 v67, v196, v197
	v_add_u32_e32 v160, 0x9000, v230
	global_load_dwordx4 v[214:217], v160, s[20:21]
	global_load_dwordx4 v[218:221], v160, s[20:21] offset:16
	global_load_dwordx4 v[222:225], v160, s[20:21] offset:32
	global_load_dwordx4 v[226:229], v160, s[20:21] offset:48
	v_cvt_pk_bf16_f32 v76, v76, v77
	v_cvt_pk_bf16_f32 v77, v78, v79
	v_cvt_pk_bf16_f32 v78, v68, v69
	v_cvt_pk_bf16_f32 v79, v70, v71
	global_store_dwordx4 v233, v[76:79], s[28:29]
	v_cvt_pk_bf16_f32 v72, v72, v73
	v_cvt_pk_bf16_f32 v73, v74, v75
	v_cvt_pk_bf16_f32 v74, v64, v65
	v_cvt_pk_bf16_f32 v75, v66, v67
	global_store_dwordx4 v233, v[72:75], s[28:29] offset:64
	s_waitcnt vmcnt(8)
; __device__ __forceinline__ u32x4 pack8(f32x4 a, f32x4 b) { u32x4 w; w.x = cvt_pk_bf16(a[0], a[1]); w.y = cvt_pk_bf16(a[2], a[3]); w.z = cvt_pk_bf16(b[0], b[1]); w.w = cvt_pk_bf16(b[2], b[3]); return w; }
; __device__ __forceinline__ bf16x8 pack8(const f32x16& p, int b) { u32x4 w; w.x = cvtpk(p[b], p[b + 1]); w.y = cvtpk(p[b + 2], p[b + 3]); w.z = cvtpk(p[b + 4], p[b + 5]); w.w = cvtpk(p[b + 6], p[b + 7]); return __builtin_bit_cast(bf16x8, w); }
;     __device__ __forceinline__ void operator()(const f32x4 (&acc)[2][2][4][2], const Unit& u, int wr, int wc, int fr, int fq) const {
;     ...
;                 if (rp) {
;                     const int t = row & (T - 1);
;                     const f32x4* rt = (const f32x4*)(rope + ((size_t)t * 32 + 8 * fq) * 2);
;                     f32x4 o1[2], o2[2];
; #pragma unroll
;                     for (int n = 0; n < 2; ++n) {
;                         const f32x4 cs0 = rt[2 * n], cs1 = rt[2 * n + 1];
;                         const f32x4 x1 = acc[ai][0][m][n] * rs, x2 = acc[ai][1][m][n] * rs;
;                         o1[n][0] = x1[0] * cs0[0] - x2[0] * cs0[1]; o2[n][0] = x2[0] * cs0[0] + x1[0] * cs0[1];
;                         o1[n][1] = x1[1] * cs0[2] - x2[1] * cs0[3]; o2[n][1] = x2[1] * cs0[2] + x1[1] * cs0[3];
;                         o1[n][2] = x1[2] * cs1[0] - x2[2] * cs1[1]; o2[n][2] = x2[2] * cs1[0] + x1[2] * cs1[1];
;                         o1[n][3] = x1[3] * cs1[2] - x2[3] * cs1[3]; o2[n][3] = x2[3] * cs1[2] + x1[3] * cs1[3];
;                     }
;                     bf16_t* rowp = dst + (size_t)row * 512 + half * 256 + wc * 64 + 8 * fq;
;                     *(u32x4*)(rowp) = pack8(o1[0], o1[1]);
;                     *(u32x4*)(rowp + 32) = pack8(o2[0], o2[1]);
	v_fmamk_f32 v170, v170, 0x3a800000, v168
	v_rsq_f32_e32 v170, v170
	v_add_u32_e32 v233, 0x20000, v232
	v_mul_f32_e32 v170, v231, v170
	v_pk_mul_f32 v[60:61], v[60:61], v[170:171] op_sel_hi:[1,0]
	v_pk_mul_f32 v[62:63], v[62:63], v[170:171] op_sel_hi:[1,0]
	v_pk_mul_f32 v[52:53], v[52:53], v[170:171] op_sel_hi:[1,0]
	v_pk_mul_f32 v[54:55], v[54:55], v[170:171] op_sel_hi:[1,0]
	v_pk_mul_f32 v[56:57], v[56:57], v[170:171] op_sel_hi:[1,0]
	v_pk_mul_f32 v[58:59], v[58:59], v[170:171] op_sel_hi:[1,0]
	v_pk_mul_f32 v[48:49], v[48:49], v[170:171] op_sel_hi:[1,0]
	v_pk_mul_f32 v[50:51], v[50:51], v[170:171] op_sel_hi:[1,0]
	v_mul_f32_e32 v194, v60, v178
	v_mul_f32_e32 v195, v56, v179
	v_mul_f32_e32 v196, v56, v178
	v_mul_f32_e32 v197, v60, v179
	v_sub_f32_e32 v60, v194, v195
	v_add_f32_e32 v56, v196, v197
	v_mul_f32_e32 v194, v61, v180
	v_mul_f32_e32 v195, v57, v181
	v_mul_f32_e32 v196, v57, v180
	v_mul_f32_e32 v197, v61, v181
	v_sub_f32_e32 v61, v194, v195
	v_add_f32_e32 v57, v196, v197
	v_mul_f32_e32 v194, v62, v182
	v_mul_f32_e32 v195, v58, v183
	v_mul_f32_e32 v196, v58, v182
	v_mul_f32_e32 v197, v62, v183
	v_sub_f32_e32 v62, v194, v195
	v_add_f32_e32 v58, v196, v197
	v_mul_f32_e32 v194, v63, v184
	v_mul_f32_e32 v195, v59, v185
	v_mul_f32_e32 v196, v59, v184
	v_mul_f32_e32 v197, v63, v185
	v_sub_f32_e32 v63, v194, v195
	v_add_f32_e32 v59, v196, v197
	v_mul_f32_e32 v194, v52, v186
	v_mul_f32_e32 v195, v48, v187
	v_mul_f32_e32 v196, v48, v186
	v_mul_f32_e32 v197, v52, v187
	v_sub_f32_e32 v52, v194, v195
	v_add_f32_e32 v48, v196, v197
	v_mul_f32_e32 v194, v53, v188
	v_mul_f32_e32 v195, v49, v189
	v_mul_f32_e32 v196, v49, v188
	v_mul_f32_e32 v197, v53, v189
	v_sub_f32_e32 v53, v194, v195
	v_add_f32_e32 v49, v196, v197
	v_mul_f32_e32 v194, v54, v190
	v_mul_f32_e32 v195, v50, v191
	v_mul_f32_e32 v196, v50, v190
	v_mul_f32_e32 v197, v54, v191
	v_sub_f32_e32 v54, v194, v195
	v_add_f32_e32 v50, v196, v197
	v_mul_f32_e32 v194, v55, v192
	v_mul_f32_e32 v195, v51, v193
	v_mul_f32_e32 v196, v51, v192
	v_mul_f32_e32 v197, v55, v193
	v_sub_f32_e32 v55, v194, v195
	v_add_f32_e32 v51, v196, v197
	v_add_u32_e32 v160, 0xa000, v230
	global_load_dwordx4 v[178:181], v160, s[20:21]
	global_load_dwordx4 v[182:185], v160, s[20:21] offset:16
	global_load_dwordx4 v[186:189], v160, s[20:21] offset:32
	global_load_dwordx4 v[190:193], v160, s[20:21] offset:48
	v_cvt_pk_bf16_f32 v60, v60, v61
	v_cvt_pk_bf16_f32 v61, v62, v63
	v_cvt_pk_bf16_f32 v62, v52, v53
	v_cvt_pk_bf16_f32 v63, v54, v55
	global_store_dwordx4 v233, v[60:63], s[28:29]
	v_cvt_pk_bf16_f32 v56, v56, v57
	v_cvt_pk_bf16_f32 v57, v58, v59
	v_cvt_pk_bf16_f32 v58, v48, v49
	v_cvt_pk_bf16_f32 v59, v50, v51
	global_store_dwordx4 v233, v[56:59], s[28:29] offset:64
	s_waitcnt vmcnt(8)
	v_fmamk_f32 v172, v172, 0x3a800000, v168
	v_rsq_f32_e32 v172, v172
	v_add_u32_e32 v233, 0x24000, v232
	v_mul_f32_e32 v172, v231, v172
	v_pk_mul_f32 v[44:45], v[44:45], v[172:173] op_sel_hi:[1,0]
	v_pk_mul_f32 v[46:47], v[46:47], v[172:173] op_sel_hi:[1,0]
	v_pk_mul_f32 v[36:37], v[36:37], v[172:173] op_sel_hi:[1,0]
	v_pk_mul_f32 v[38:39], v[38:39], v[172:173] op_sel_hi:[1,0]
	v_pk_mul_f32 v[40:41], v[40:41], v[172:173] op_sel_hi:[1,0]
	v_pk_mul_f32 v[42:43], v[42:43], v[172:173] op_sel_hi:[1,0]
	v_pk_mul_f32 v[32:33], v[32:33], v[172:173] op_sel_hi:[1,0]
	v_pk_mul_f32 v[34:35], v[34:35], v[172:173] op_sel_hi:[1,0]
	v_mul_f32_e32 v194, v44, v214
	v_mul_f32_e32 v195, v40, v215
	v_mul_f32_e32 v196, v40, v214
	v_mul_f32_e32 v197, v44, v215
	v_sub_f32_e32 v44, v194, v195
	v_add_f32_e32 v40, v196, v197
	v_mul_f32_e32 v194, v45, v216
	v_mul_f32_e32 v195, v41, v217
	v_mul_f32_e32 v196, v41, v216
	v_mul_f32_e32 v197, v45, v217
	v_sub_f32_e32 v45, v194, v195
	v_add_f32_e32 v41, v196, v197
	v_mul_f32_e32 v194, v46, v218
	v_mul_f32_e32 v195, v42, v219
	v_mul_f32_e32 v196, v42, v218
	v_mul_f32_e32 v197, v46, v219
	v_sub_f32_e32 v46, v194, v195
	v_add_f32_e32 v42, v196, v197
	v_mul_f32_e32 v194, v47, v220
	v_mul_f32_e32 v195, v43, v221
	v_mul_f32_e32 v196, v43, v220
	v_mul_f32_e32 v197, v47, v221
	v_sub_f32_e32 v47, v194, v195
	v_add_f32_e32 v43, v196, v197
	v_mul_f32_e32 v194, v36, v222
	v_mul_f32_e32 v195, v32, v223
	v_mul_f32_e32 v196, v32, v222
	v_mul_f32_e32 v197, v36, v223
	v_sub_f32_e32 v36, v194, v195
	v_add_f32_e32 v32, v196, v197
	v_mul_f32_e32 v194, v37, v224
	v_mul_f32_e32 v195, v33, v225
	v_mul_f32_e32 v196, v33, v224
	v_mul_f32_e32 v197, v37, v225
	v_sub_f32_e32 v37, v194, v195
	v_add_f32_e32 v33, v196, v197
	v_mul_f32_e32 v194, v38, v226
	v_mul_f32_e32 v195, v34, v227
	v_mul_f32_e32 v196, v34, v226
	v_mul_f32_e32 v197, v38, v227
	v_sub_f32_e32 v38, v194, v195
	v_add_f32_e32 v34, v196, v197
	v_mul_f32_e32 v194, v39, v228
	v_mul_f32_e32 v195, v35, v229
	v_mul_f32_e32 v196, v35, v228
	v_mul_f32_e32 v197, v39, v229
	v_sub_f32_e32 v39, v194, v195
	v_add_f32_e32 v35, v196, v197
	v_add_u32_e32 v160, 0xb000, v230
	global_load_dwordx4 v[214:217], v160, s[20:21]
	global_load_dwordx4 v[218:221], v160, s[20:21] offset:16
	global_load_dwordx4 v[222:225], v160, s[20:21] offset:32
	global_load_dwordx4 v[226:229], v160, s[20:21] offset:48
	v_cvt_pk_bf16_f32 v44, v44, v45
	v_cvt_pk_bf16_f32 v45, v46, v47
	v_cvt_pk_bf16_f32 v46, v36, v37
	v_cvt_pk_bf16_f32 v47, v38, v39
	global_store_dwordx4 v233, v[44:47], s[28:29]
	v_cvt_pk_bf16_f32 v40, v40, v41
	v_cvt_pk_bf16_f32 v41, v42, v43
	v_cvt_pk_bf16_f32 v42, v32, v33
	v_cvt_pk_bf16_f32 v43, v34, v35
	global_store_dwordx4 v233, v[40:43], s[28:29] offset:64
	s_waitcnt vmcnt(8)
; __device__ __forceinline__ u32x4 pack8(f32x4 a, f32x4 b) { u32x4 w; w.x = cvt_pk_bf16(a[0], a[1]); w.y = cvt_pk_bf16(a[2], a[3]); w.z = cvt_pk_bf16(b[0], b[1]); w.w = cvt_pk_bf16(b[2], b[3]); return w; }
; __device__ __forceinline__ bf16x8 pack8(const f32x16& p, int b) { u32x4 w; w.x = cvtpk(p[b], p[b + 1]); w.y = cvtpk(p[b + 2], p[b + 3]); w.z = cvtpk(p[b + 4], p[b + 5]); w.w = cvtpk(p[b + 6], p[b + 7]); return __builtin_bit_cast(bf16x8, w); }
;     __device__ __forceinline__ void operator()(const f32x4 (&acc)[2][2][4][2], const Unit& u, int wr, int wc, int fr, int fq) const {
;     ...
;                 const int row = u.pm * BM + ai * HALF + wr * 64 + m * 16 + fr;
;                 const float rs = __builtin_amdgcn_rsqf(ssq[row] * (1.0f / 1024.0f) + EPS) * sc;
;                 if (rp) {
;                     const int t = row & (T - 1);
;                     const f32x4* rt = (const f32x4*)(rope + ((size_t)t * 32 + 8 * fq) * 2);
;                     f32x4 o1[2], o2[2];
; #pragma unroll
;                     for (int n = 0; n < 2; ++n) {
;                         const f32x4 cs0 = rt[2 * n], cs1 = rt[2 * n + 1];
;                         const f32x4 x1 = acc[ai][0][m][n] * rs, x2 = acc[ai][1][m][n] * rs;
;                         o1[n][0] = x1[0] * cs0[0] - x2[0] * cs0[1]; o2[n][0] = x2[0] * cs0[0] + x1[0] * cs0[1];
;                         o1[n][1] = x1[1] * cs0[2] - x2[1] * cs0[3]; o2[n][1] = x2[1] * cs0[2] + x1[1] * cs0[3];
;                         o1[n][2] = x1[2] * cs1[0] - x2[2] * cs1[1]; o2[n][2] = x2[2] * cs1[0] + x1[2] * cs1[1];
;                         o1[n][3] = x1[3] * cs1[2] - x2[3] * cs1[3]; o2[n][3] = x2[3] * cs1[2] + x1[3] * cs1[3];
;                     }
;                     bf16_t* rowp = dst + (size_t)row * 512 + half * 256 + wc * 64 + 8 * fq;
;                     *(u32x4*)(rowp) = pack8(o1[0], o1[1]);
;                     *(u32x4*)(rowp + 32) = pack8(o2[0], o2[1]);
	v_fmamk_f32 v174, v174, 0x3a800000, v168
	v_rsq_f32_e32 v174, v174
	v_add_u32_e32 v233, 0x28000, v232
	v_mul_f32_e32 v174, v231, v174
	v_pk_mul_f32 v[28:29], v[28:29], v[174:175] op_sel_hi:[1,0]
	v_pk_mul_f32 v[30:31], v[30:31], v[174:175] op_sel_hi:[1,0]
	v_pk_mul_f32 v[20:21], v[20:21], v[174:175] op_sel_hi:[1,0]
	v_pk_mul_f32 v[22:23], v[22:23], v[174:175] op_sel_hi:[1,0]
	v_pk_mul_f32 v[24:25], v[24:25], v[174:175] op_sel_hi:[1,0]
	v_pk_mul_f32 v[26:27], v[26:27], v[174:175] op_sel_hi:[1,0]
	v_pk_mul_f32 v[16:17], v[16:17], v[174:175] op_sel_hi:[1,0]
	v_pk_mul_f32 v[18:19], v[18:19], v[174:175] op_sel_hi:[1,0]
	v_mul_f32_e32 v194, v28, v178
	v_mul_f32_e32 v195, v24, v179
	v_mul_f32_e32 v196, v24, v178
	v_mul_f32_e32 v197, v28, v179
	v_sub_f32_e32 v28, v194, v195
	v_add_f32_e32 v24, v196, v197
	v_mul_f32_e32 v194, v29, v180
	v_mul_f32_e32 v195, v25, v181
	v_mul_f32_e32 v196, v25, v180
	v_mul_f32_e32 v197, v29, v181
	v_sub_f32_e32 v29, v194, v195
	v_add_f32_e32 v25, v196, v197
	v_mul_f32_e32 v194, v30, v182
	v_mul_f32_e32 v195, v26, v183
	v_mul_f32_e32 v196, v26, v182
	v_mul_f32_e32 v197, v30, v183
	v_sub_f32_e32 v30, v194, v195
	v_add_f32_e32 v26, v196, v197
	v_mul_f32_e32 v194, v31, v184
	v_mul_f32_e32 v195, v27, v185
	v_mul_f32_e32 v196, v27, v184
	v_mul_f32_e32 v197, v31, v185
	v_sub_f32_e32 v31, v194, v195
	v_add_f32_e32 v27, v196, v197
	v_mul_f32_e32 v194, v20, v186
	v_mul_f32_e32 v195, v16, v187
	v_mul_f32_e32 v196, v16, v186
	v_mul_f32_e32 v197, v20, v187
	v_sub_f32_e32 v20, v194, v195
	v_add_f32_e32 v16, v196, v197
	v_mul_f32_e32 v194, v21, v188
	v_mul_f32_e32 v195, v17, v189
	v_mul_f32_e32 v196, v17, v188
	v_mul_f32_e32 v197, v21, v189
	v_sub_f32_e32 v21, v194, v195
	v_add_f32_e32 v17, v196, v197
	v_mul_f32_e32 v194, v22, v190
	v_mul_f32_e32 v195, v18, v191
	v_mul_f32_e32 v196, v18, v190
	v_mul_f32_e32 v197, v22, v191
	v_sub_f32_e32 v22, v194, v195
	v_add_f32_e32 v18, v196, v197
	v_mul_f32_e32 v194, v23, v192
	v_mul_f32_e32 v195, v19, v193
	v_mul_f32_e32 v196, v19, v192
	v_mul_f32_e32 v197, v23, v193
	v_sub_f32_e32 v23, v194, v195
	v_add_f32_e32 v19, v196, v197
	v_cvt_pk_bf16_f32 v28, v28, v29
	v_cvt_pk_bf16_f32 v29, v30, v31
	v_cvt_pk_bf16_f32 v30, v20, v21
	v_cvt_pk_bf16_f32 v31, v22, v23
	global_store_dwordx4 v233, v[28:31], s[28:29]
	v_cvt_pk_bf16_f32 v24, v24, v25
	v_cvt_pk_bf16_f32 v25, v26, v27
	v_cvt_pk_bf16_f32 v26, v16, v17
	v_cvt_pk_bf16_f32 v27, v18, v19
	global_store_dwordx4 v233, v[24:27], s[28:29] offset:64
	s_waitcnt vmcnt(4)
	v_fmamk_f32 v176, v176, 0x3a800000, v168
	v_rsq_f32_e32 v176, v176
	v_add_u32_e32 v233, 0x2c000, v232
	v_mul_f32_e32 v176, v231, v176
	v_pk_mul_f32 v[12:13], v[12:13], v[176:177] op_sel_hi:[1,0]
	v_pk_mul_f32 v[14:15], v[14:15], v[176:177] op_sel_hi:[1,0]
	v_pk_mul_f32 v[4:5], v[4:5], v[176:177] op_sel_hi:[1,0]
	v_pk_mul_f32 v[6:7], v[6:7], v[176:177] op_sel_hi:[1,0]
	v_pk_mul_f32 v[8:9], v[8:9], v[176:177] op_sel_hi:[1,0]
	v_pk_mul_f32 v[10:11], v[10:11], v[176:177] op_sel_hi:[1,0]
	v_pk_mul_f32 v[0:1], v[0:1], v[176:177] op_sel_hi:[1,0]
	v_pk_mul_f32 v[2:3], v[2:3], v[176:177] op_sel_hi:[1,0]
	v_mul_f32_e32 v194, v12, v214
	v_mul_f32_e32 v195, v8, v215
	v_mul_f32_e32 v196, v8, v214
	v_mul_f32_e32 v197, v12, v215
	v_sub_f32_e32 v12, v194, v195
	v_add_f32_e32 v8, v196, v197
	v_mul_f32_e32 v194, v13, v216
	v_mul_f32_e32 v195, v9, v217
	v_mul_f32_e32 v196, v9, v216
	v_mul_f32_e32 v197, v13, v217
	v_sub_f32_e32 v13, v194, v195
	v_add_f32_e32 v9, v196, v197
	v_mul_f32_e32 v194, v14, v218
	v_mul_f32_e32 v195, v10, v219
	v_mul_f32_e32 v196, v10, v218
	v_mul_f32_e32 v197, v14, v219
	v_sub_f32_e32 v14, v194, v195
	v_add_f32_e32 v10, v196, v197
	v_mul_f32_e32 v194, v15, v220
	v_mul_f32_e32 v195, v11, v221
	v_mul_f32_e32 v196, v11, v220
	v_mul_f32_e32 v197, v15, v221
	v_sub_f32_e32 v15, v194, v195
	v_add_f32_e32 v11, v196, v197
	v_mul_f32_e32 v194, v4, v222
	v_mul_f32_e32 v195, v0, v223
	v_mul_f32_e32 v196, v0, v222
	v_mul_f32_e32 v197, v4, v223
	v_sub_f32_e32 v4, v194, v195
	v_add_f32_e32 v0, v196, v197
	v_mul_f32_e32 v194, v5, v224
	v_mul_f32_e32 v195, v1, v225
	v_mul_f32_e32 v196, v1, v224
	v_mul_f32_e32 v197, v5, v225
	v_sub_f32_e32 v5, v194, v195
	v_add_f32_e32 v1, v196, v197
	v_mul_f32_e32 v194, v6, v226
	v_mul_f32_e32 v195, v2, v227
	v_mul_f32_e32 v196, v2, v226
	v_mul_f32_e32 v197, v6, v227
	v_sub_f32_e32 v6, v194, v195
	v_add_f32_e32 v2, v196, v197
	v_mul_f32_e32 v194, v7, v228
	v_mul_f32_e32 v195, v3, v229
	v_mul_f32_e32 v196, v3, v228
	v_mul_f32_e32 v197, v7, v229
	v_sub_f32_e32 v7, v194, v195
	v_add_f32_e32 v3, v196, v197
	v_cvt_pk_bf16_f32 v12, v12, v13
	v_cvt_pk_bf16_f32 v13, v14, v15
	v_cvt_pk_bf16_f32 v14, v4, v5
	v_cvt_pk_bf16_f32 v15, v6, v7
	global_store_dwordx4 v233, v[12:15], s[28:29]
	v_cvt_pk_bf16_f32 v8, v8, v9
	v_cvt_pk_bf16_f32 v9, v10, v11
	v_cvt_pk_bf16_f32 v10, v0, v1
	v_cvt_pk_bf16_f32 v11, v2, v3
	global_store_dwordx4 v233, v[8:11], s[28:29] offset:64
.Lp1_done:
	s_andn2_b64 vcc, exec, s[4:5]
	s_mov_b64 s[4:5], -1
	s_cbranch_vccnz .LBB0_355
	s_branch .LBB0_395
.LBB0_395:
	s_andn2_b64 vcc, exec, s[0:1]
	s_cbranch_vccnz .LBB0_354
	s_barrier
	s_branch .LBB0_354

.LBB0_508:
.LBB0_509:
	s_add_i32 s20, s2, 0xffffc000
	s_and_b32 s20, s20, 0xc000
	v_add_u32_e32 v238, s20, v234
	s_add_i32 s20, s65, s20
	v_mfma_f32_32x32x16_bf16 v[0:15], v[160:163], v[128:131], v[0:15]
	ds_read_b64_tr_b16 v[196:197], v238
	ds_read_b64_tr_b16 v[198:199], v238 offset:512
	v_add_u32_e32 v96, s20, v228
	v_add_u32_e32 v97, s20, v229
	v_add_u32_e32 v98, s20, v230
	v_mfma_f32_32x32x16_bf16 v[0:15], v[164:167], v[132:135], v[0:15]
	ds_read_b64_tr_b16 v[192:193], v238 offset:1024
	ds_read_b64_tr_b16 v[194:195], v238 offset:1536
	v_mfma_f32_32x32x16_bf16 v[32:47], v[160:163], v[136:139], v[32:47]
	ds_read_b64_tr_b16 v[188:189], v238 offset:4096
	ds_read_b64_tr_b16 v[190:191], v238 offset:4608
	v_mfma_f32_32x32x16_bf16 v[32:47], v[164:167], v[140:143], v[32:47]
	ds_read_b64_tr_b16 v[184:185], v238 offset:5120
	ds_read_b64_tr_b16 v[186:187], v238 offset:5632
	v_mfma_f32_32x32x16_bf16 v[48:63], v[160:163], v[144:147], v[48:63]
	ds_read_b64_tr_b16 v[180:181], v238 offset:8192
	ds_read_b64_tr_b16 v[182:183], v238 offset:8704
	v_mfma_f32_32x32x16_bf16 v[48:63], v[164:167], v[148:151], v[48:63]
	ds_read_b64_tr_b16 v[176:177], v238 offset:9216
	ds_read_b64_tr_b16 v[178:179], v238 offset:9728
	ds_read_b128 v[128:131], v96 offset:4096
	v_mfma_f32_32x32x16_bf16 v[16:31], v[160:163], v[152:155], v[16:31]
	ds_read_b64_tr_b16 v[172:173], v238 offset:12288
	ds_read_b64_tr_b16 v[174:175], v238 offset:12800
	v_mfma_f32_32x32x16_bf16 v[16:31], v[164:167], v[156:159], v[16:31]
	ds_read_b64_tr_b16 v[168:169], v238 offset:13312
	ds_read_b64_tr_b16 v[170:171], v238 offset:13824
	ds_read_b128 v[132:135], v97 offset:4096
	ds_read_b128 v[136:139], v98 offset:4096
	v_add_u32_e32 v96, s20, v231
	ds_read_b128 v[140:143], v96 offset:4096
	s_waitcnt lgkmcnt(7)
	v_mfma_f32_32x32x16_bf16 v[96:111], v[128:131], v[112:115], v[64:79]
	v_max3_f32 v144, v80, v81, v82
	v_max3_f32 v145, v83, v84, v85
	s_waitcnt lgkmcnt(2)
	v_mfma_f32_32x32x16_bf16 v[96:111], v[132:135], v[116:119], v[96:111]
	v_max3_f32 v128, v144, v86, v87
	v_max3_f32 v129, v145, v88, v89
	s_waitcnt lgkmcnt(1)
	v_mfma_f32_32x32x16_bf16 v[96:111], v[136:139], v[120:123], v[96:111]
	v_max3_f32 v128, v128, v90, v91
	v_max3_f32 v129, v129, v92, v93
	s_nop 0
	v_max3_f32 v128, v128, v94, v95
	s_waitcnt lgkmcnt(0)
	v_mfma_f32_32x32x16_bf16 v[96:111], v[140:143], v[124:127], v[96:111]
	v_max_f32_e32 v128, v128, v129
	ds_bpermute_b32 v129, v214, v128
	s_andn2_b64 vcc, exec, s[0:1]
	s_cbranch_vccz .LBB0_522
.LBB0_510:
	v_exp_f32_e32 v140, v80
	v_exp_f32_e32 v144, v81
	v_exp_f32_e32 v138, v82
	v_exp_f32_e32 v141, v83
	v_exp_f32_e32 v142, v84
	v_exp_f32_e32 v145, v85
	v_exp_f32_e32 v139, v86
	v_exp_f32_e32 v143, v87
	v_exp_f32_e32 v132, v88
	v_exp_f32_e32 v136, v89
	v_add_f32_e32 v80, v138, v140
	v_add_f32_e32 v81, v141, v144
	v_exp_f32_e32 v130, v90
	v_exp_f32_e32 v133, v91
	v_add_f32_e32 v80, v142, v80
	v_add_f32_e32 v81, v145, v81
	v_exp_f32_e32 v134, v92
	v_exp_f32_e32 v137, v93
	v_add_f32_e32 v80, v139, v80
	v_add_f32_e32 v81, v143, v81
	v_exp_f32_e32 v131, v94
	v_exp_f32_e32 v135, v95
	v_add_f32_e32 v80, v132, v80
	v_add_f32_e32 v81, v136, v81
	v_add_f32_e32 v80, v130, v80
	v_add_f32_e32 v81, v133, v81
	v_add_f32_e32 v80, v134, v80
	v_add_f32_e32 v81, v137, v81
	v_add_f32_e32 v80, v131, v80
	v_add_f32_e32 v81, v135, v81
	v_add_f32_e32 v80, v80, v81
	v_add_f32_e32 v235, v235, v80
	s_waitcnt lgkmcnt(0)
	v_max_f32_e32 v80, v128, v129
	v_cmp_lt_f32_e32 vcc, s67, v80
	s_cmp_lg_u64 vcc, 0
	s_cselect_b64 s[0:1], -1, 0
	s_cbranch_vccnz .LBB0_525
.LBB0_512:
	v_cvt_pk_bf16_f32 v156, v140, v144
	v_cvt_pk_bf16_f32 v157, v138, v141
	v_cvt_pk_bf16_f32 v158, v142, v145
	v_cvt_pk_bf16_f32 v159, v139, v143
	v_cvt_pk_bf16_f32 v162, v132, v136
	v_cvt_pk_bf16_f32 v163, v130, v133
	v_cvt_pk_bf16_f32 v164, v134, v137
	v_cvt_pk_bf16_f32 v165, v131, v135
	s_and_b32 s20, s2, 0xc000
	s_add_i32 s20, s65, s20
	v_mfma_f32_32x32x16_bf16 v[0:15], v[156:159], v[196:199], v[0:15]
	ds_read_b64_tr_b16 v[128:129], v238 offset:2048
	ds_read_b64_tr_b16 v[130:131], v238 offset:2560
	v_exp_f32_e32 v160, v96
	v_exp_f32_e32 v161, v97
	v_add_u32_e32 v152, s20, v228
	v_add_u32_e32 v239, s20, v229
	v_add_u32_e32 v240, s20, v230
	v_mfma_f32_32x32x16_bf16 v[0:15], v[162:165], v[192:195], v[0:15]
	ds_read_b64_tr_b16 v[132:133], v238 offset:3072
	ds_read_b64_tr_b16 v[134:135], v238 offset:3584
	v_exp_f32_e32 v166, v98
	v_exp_f32_e32 v167, v99
	v_mfma_f32_32x32x16_bf16 v[32:47], v[156:159], v[188:191], v[32:47]
	ds_read_b64_tr_b16 v[136:137], v238 offset:6144
	ds_read_b64_tr_b16 v[138:139], v238 offset:6656
	v_exp_f32_e32 v192, v100
	v_exp_f32_e32 v193, v101
	v_mfma_f32_32x32x16_bf16 v[32:47], v[162:165], v[184:187], v[32:47]
	ds_read_b64_tr_b16 v[140:141], v238 offset:7168
	ds_read_b64_tr_b16 v[142:143], v238 offset:7680
	v_exp_f32_e32 v188, v102
	v_exp_f32_e32 v189, v103
	v_mfma_f32_32x32x16_bf16 v[48:63], v[156:159], v[180:183], v[48:63]
	ds_read_b64_tr_b16 v[144:145], v238 offset:10240
	ds_read_b64_tr_b16 v[146:147], v238 offset:10752
	v_exp_f32_e32 v184, v104
	v_exp_f32_e32 v185, v105
	v_mfma_f32_32x32x16_bf16 v[48:63], v[162:165], v[176:179], v[48:63]
	ds_read_b64_tr_b16 v[148:149], v238 offset:11264
	ds_read_b64_tr_b16 v[150:151], v238 offset:11776
	ds_read_b128 v[180:183], v152
	v_exp_f32_e32 v186, v106
	v_exp_f32_e32 v187, v107
	v_mfma_f32_32x32x16_bf16 v[16:31], v[156:159], v[172:175], v[16:31]
	ds_read_b64_tr_b16 v[152:153], v238 offset:14336
	ds_read_b64_tr_b16 v[154:155], v238 offset:14848
	v_exp_f32_e32 v176, v108
	v_exp_f32_e32 v177, v109
	v_mfma_f32_32x32x16_bf16 v[16:31], v[162:165], v[168:171], v[16:31]
	ds_read_b64_tr_b16 v[156:157], v238 offset:15360
	ds_read_b64_tr_b16 v[158:159], v238 offset:15872
	v_add_f32_e32 v162, v166, v160
	v_add_f32_e32 v163, v167, v161
	v_exp_f32_e32 v178, v110
	v_exp_f32_e32 v179, v111
	v_pk_add_f32 v[164:165], v[192:193], v[162:163]
	ds_read_b128 v[168:171], v239
	ds_read_b128 v[172:175], v240
	v_pk_add_f32 v[164:165], v[188:189], v[164:165]
	v_cvt_pk_bf16_f32 v160, v160, v161
	v_cvt_pk_bf16_f32 v161, v166, v167
	v_pk_add_f32 v[166:167], v[184:185], v[164:165]
	v_cvt_pk_bf16_f32 v162, v192, v193
	v_pk_add_f32 v[166:167], v[186:187], v[166:167]
	v_cvt_pk_bf16_f32 v163, v188, v189
	v_cvt_pk_bf16_f32 v164, v184, v185
	v_cvt_pk_bf16_f32 v165, v186, v187
	v_pk_add_f32 v[184:185], v[176:177], v[166:167]
	v_cvt_pk_bf16_f32 v166, v176, v177
	v_cvt_pk_bf16_f32 v167, v178, v179
	v_pk_add_f32 v[176:177], v[178:179], v[184:185]
	s_waitcnt lgkmcnt(6)
	v_mfma_f32_32x32x16_bf16 v[80:95], v[180:183], v[112:115], v[64:79]
	v_max3_f32 v178, v96, v97, v98
	v_add_f32_e32 v96, v176, v177
	v_add_f32_e32 v235, v235, v96
	v_add_u32_e32 v96, s20, v231
	v_max3_f32 v100, v99, v100, v101
	ds_read_b128 v[96:99], v96
	s_waitcnt lgkmcnt(2)
	v_mfma_f32_32x32x16_bf16 v[80:95], v[168:171], v[116:119], v[80:95]
	v_max3_f32 v101, v178, v102, v103
	v_max3_f32 v100, v100, v104, v105
	s_waitcnt lgkmcnt(1)
	v_mfma_f32_32x32x16_bf16 v[80:95], v[172:175], v[120:123], v[80:95]
	v_max3_f32 v101, v101, v106, v107
	v_max3_f32 v100, v100, v108, v109
	s_nop 0
	v_max3_f32 v101, v101, v110, v111
	v_max_f32_e32 v100, v101, v100
	s_waitcnt lgkmcnt(0)
	v_mfma_f32_32x32x16_bf16 v[80:95], v[96:99], v[124:127], v[80:95]
	ds_bpermute_b32 v101, v214, v100
	s_waitcnt lgkmcnt(0)
	v_max_f32_e32 v96, v100, v101
	s_addk_i32 s2, 0x4000
	s_add_i32 s3, s3, -1
	s_cmp_ge_u32 s37, s84
	s_cbranch_scc1 .LBB0_527
	s_mov_b32 s76, s37
	s_branch .LBB0_502

;     __device__ __forceinline__ void operator()(const f32x4 (&acc)[2][2][4][2], const Unit& u, int wr, int wc, int fr, int fq) const {
;     ...
;                 const int row = u.pm * BM + ai * HALF + wr * 64 + m * 16 + fr;
;                 const float rs = __builtin_amdgcn_rsqf(ssq[row] * (1.0f / 1024.0f) + EPS);
; template <class Epi, class Sched, bool ALIGN_EPI = false, bool SP2 = false>
; __device__ __forceinline__ void gemm_phase(PG8_LAS unsigned char* lds, const Gemm g, const Sched& S, const Epi& E) {
;     ...
;         for (int a = 0; a < 2; ++a)
; #pragma unroll
;             for (int b = 0; b < 2; ++b)
; #pragma unroll
;                 for (int m = 0; m < 4; ++m)
; #pragma unroll
;                     for (int n = 0; n < 2; ++n) acc[a][b][m][n] = (f32x4){0.f, 0.f, 0.f, 0.f};
;         cur = nxt; cA = nA; cB = nB; ++ui;
.LBB0_707:
	s_ashr_i32 s17, s16, 31
	s_lshl_b64 s[18:19], s[16:17], 19
	s_add_u32 s18, s88, s18
	s_addc_u32 s19, s89, s19
	s_and_b64 s[24:25], s[6:7], exec
	s_cselect_b32 s3, s19, s27
	s_cselect_b32 s17, s18, s26
	s_ashr_i32 s15, s14, 31
	s_lshl_b64 s[24:25], s[14:15], 19
	s_add_u32 s24, s33, s24
	s_addc_u32 s25, s34, s25
	s_and_b64 s[30:31], s[6:7], exec
	s_cselect_b32 s15, s25, s29
	s_cselect_b32 s23, s24, s28
	s_add_u32 s26, s26, 0x40080
	s_addc_u32 s27, s27, 0
	s_add_u32 s49, s28, 0x100
	v_mov_b32_e32 v4, 0
	s_addc_u32 s50, s29, 0
	s_mov_b32 s51, -2
	v_mov_b32_e32 v5, v4
	v_mov_b32_e32 v6, v4
	v_mov_b32_e32 v7, v4
	v_mov_b32_e32 v12, v4
	v_mov_b32_e32 v13, v4
	v_mov_b32_e32 v14, v4
	v_mov_b32_e32 v15, v4
	v_mov_b32_e32 v20, v4
	v_mov_b32_e32 v21, v4
	v_mov_b32_e32 v22, v4
	v_mov_b32_e32 v23, v4
	v_mov_b32_e32 v28, v4
	v_mov_b32_e32 v29, v4
	v_mov_b32_e32 v30, v4
	v_mov_b32_e32 v31, v4
	v_mov_b32_e32 v36, v4
	v_mov_b32_e32 v37, v4
	v_mov_b32_e32 v38, v4
	v_mov_b32_e32 v39, v4
	v_mov_b32_e32 v44, v4
	v_mov_b32_e32 v45, v4
	v_mov_b32_e32 v46, v4
	v_mov_b32_e32 v47, v4
	v_mov_b32_e32 v52, v4
	v_mov_b32_e32 v53, v4
	v_mov_b32_e32 v54, v4
	v_mov_b32_e32 v55, v4
	v_mov_b32_e32 v60, v4
	v_mov_b32_e32 v61, v4
	v_mov_b32_e32 v62, v4
	v_mov_b32_e32 v63, v4
	v_mov_b32_e32 v0, v4
	v_mov_b32_e32 v1, v4
	v_mov_b32_e32 v2, v4
	v_mov_b32_e32 v3, v4
	v_mov_b32_e32 v8, v4
	v_mov_b32_e32 v9, v4
	v_mov_b32_e32 v10, v4
	v_mov_b32_e32 v11, v4
	v_mov_b32_e32 v16, v4
	v_mov_b32_e32 v17, v4
	v_mov_b32_e32 v18, v4
	v_mov_b32_e32 v19, v4
	v_mov_b32_e32 v24, v4
	v_mov_b32_e32 v25, v4
	v_mov_b32_e32 v26, v4
	v_mov_b32_e32 v27, v4
	v_mov_b32_e32 v32, v4
	v_mov_b32_e32 v33, v4
	v_mov_b32_e32 v34, v4
	v_mov_b32_e32 v35, v4
	v_mov_b32_e32 v40, v4
	v_mov_b32_e32 v41, v4
	v_mov_b32_e32 v42, v4
	v_mov_b32_e32 v43, v4
	v_mov_b32_e32 v48, v4
	v_mov_b32_e32 v49, v4
	v_mov_b32_e32 v50, v4
	v_mov_b32_e32 v51, v4
	v_mov_b32_e32 v56, v4
	v_mov_b32_e32 v57, v4
	v_mov_b32_e32 v58, v4
	v_mov_b32_e32 v59, v4
	v_mov_b32_e32 v68, v4
	v_mov_b32_e32 v69, v4
	v_mov_b32_e32 v70, v4
	v_mov_b32_e32 v71, v4
	v_mov_b32_e32 v76, v4
	v_mov_b32_e32 v77, v4
	v_mov_b32_e32 v78, v4
	v_mov_b32_e32 v79, v4
	v_mov_b32_e32 v84, v4
	v_mov_b32_e32 v85, v4
	v_mov_b32_e32 v86, v4
	v_mov_b32_e32 v87, v4
	v_mov_b32_e32 v92, v4
	v_mov_b32_e32 v93, v4
	v_mov_b32_e32 v94, v4
	v_mov_b32_e32 v95, v4
	v_mov_b32_e32 v100, v4
	v_mov_b32_e32 v101, v4
	v_mov_b32_e32 v102, v4
	v_mov_b32_e32 v103, v4
	v_mov_b32_e32 v108, v4
	v_mov_b32_e32 v109, v4
	v_mov_b32_e32 v110, v4
	v_mov_b32_e32 v111, v4
	v_mov_b32_e32 v120, v4
	v_mov_b32_e32 v121, v4
	v_mov_b32_e32 v122, v4
	v_mov_b32_e32 v123, v4
	v_mov_b32_e32 v124, v4
	v_mov_b32_e32 v125, v4
	v_mov_b32_e32 v126, v4
	v_mov_b32_e32 v127, v4
	v_mov_b32_e32 v64, v4
	v_mov_b32_e32 v65, v4
	v_mov_b32_e32 v66, v4
	v_mov_b32_e32 v67, v4
	v_mov_b32_e32 v72, v4
	v_mov_b32_e32 v73, v4
	v_mov_b32_e32 v74, v4
	v_mov_b32_e32 v75, v4
	v_mov_b32_e32 v80, v4
	v_mov_b32_e32 v81, v4
	v_mov_b32_e32 v82, v4
	v_mov_b32_e32 v83, v4
	v_mov_b32_e32 v88, v4
	v_mov_b32_e32 v89, v4
	v_mov_b32_e32 v90, v4
	v_mov_b32_e32 v91, v4
	v_mov_b32_e32 v96, v4
	v_mov_b32_e32 v97, v4
	v_mov_b32_e32 v98, v4
	v_mov_b32_e32 v99, v4
	v_mov_b32_e32 v104, v4
	v_mov_b32_e32 v105, v4
	v_mov_b32_e32 v106, v4
	v_mov_b32_e32 v107, v4
	v_mov_b32_e32 v112, v4
	v_mov_b32_e32 v113, v4
	v_mov_b32_e32 v114, v4
	v_mov_b32_e32 v115, v4
	v_mov_b32_e32 v116, v4
	v_mov_b32_e32 v117, v4
	v_mov_b32_e32 v118, v4
	v_mov_b32_e32 v119, v4
	v_lshl_add_u32 v146, s22, 8, v148
	v_lshlrev_b32_e32 v146, 2, v146
	global_load_dword v238, v146, s[56:57]
	global_load_dword v240, v146, s[56:57] offset:64
	global_load_dword v242, v146, s[56:57] offset:128
	global_load_dword v244, v146, s[56:57] offset:192
	global_load_dword v246, v146, s[56:57] offset:512
	global_load_dword v248, v146, s[56:57] offset:576
	global_load_dword v250, v146, s[56:57] offset:640
	global_load_dword v252, v146, s[56:57] offset:704

; __device__ __forceinline__ u32x4 pack8(f32x4 a, f32x4 b) { u32x4 w; w.x = cvt_pk_bf16(a[0], a[1]); w.y = cvt_pk_bf16(a[2], a[3]); w.z = cvt_pk_bf16(b[0], b[1]); w.w = cvt_pk_bf16(b[2], b[3]); return w; }
; __device__ __forceinline__ float sigm(float x) { return __builtin_amdgcn_rcpf(1.0f + __builtin_amdgcn_exp2f(-x * LOG2E)); }
; __device__ __forceinline__ bf16x8 pack8(const f32x16& p, int b) { u32x4 w; w.x = cvtpk(p[b], p[b + 1]); w.y = cvtpk(p[b + 2], p[b + 3]); w.z = cvtpk(p[b + 4], p[b + 5]); w.w = cvtpk(p[b + 6], p[b + 7]); return __builtin_bit_cast(bf16x8, w); }
;     __device__ __forceinline__ void operator()(const f32x4 (&acc)[2][2][4][2], const Unit& u, int wr, int wc, int fr, int fq) const {
;     ...
;             for (int m = 0; m < 4; ++m) {
;                 const int row = u.pm * BM + ai * HALF + wr * 64 + m * 16 + fr;
;                 const float rs = __builtin_amdgcn_rsqf(ssq[row] * (1.0f / 1024.0f) + EPS);
;                 f32x4 o[2];
; #pragma unroll
;                 for (int n = 0; n < 2; ++n)
; #pragma unroll
;                     for (int i = 0; i < 4; ++i) { const float g = acc[ai][0][m][n][i] * rs, up = acc[ai][1][m][n][i] * rs; o[n][i] = g * sigm(g) * up; }
;                 *(u32x4*)(h + (size_t)row * DFF + u.pn * HALF + wc * 32 + 8 * fq) = pack8(o[0], o[1]);
.LBB0_711:
	v_lshl_add_u32 v146, s22, 8, v148
	s_lshl_b32 s22, s2, 8
	s_add_i32 s22, s22, s0
	s_add_u32 s22, s66, s22
	s_addc_u32 s23, s67, 0
	v_mad_u32_u24 v146, v146, s47, v136
	v_mov_b32_e32 v178, 0xbfb8aa3b
	v_mov_b32_e32 v180, 1.0
	s_andn2_b64 vcc, exec, s[6:7]
	s_mov_b64 s[6:7], -1
	s_waitcnt vmcnt(8)
	v_fmamk_f32 v238, v238, 0x3a800000, v153
	v_rsq_f32_e32 v238, v238
	v_mov_b32_e32 v147, v146
	v_pk_mul_f32 v[116:117], v[116:117], v[238:239] op_sel_hi:[1,0]
	v_pk_mul_f32 v[118:119], v[118:119], v[238:239] op_sel_hi:[1,0]
	v_pk_mul_f32 v[112:113], v[112:113], v[238:239] op_sel_hi:[1,0]
	v_pk_mul_f32 v[114:115], v[114:115], v[238:239] op_sel_hi:[1,0]
	v_pk_mul_f32 v[170:171], v[116:117], v[178:179] op_sel_hi:[1,0]
	v_pk_mul_f32 v[172:173], v[118:119], v[178:179] op_sel_hi:[1,0]
	v_pk_mul_f32 v[174:175], v[112:113], v[178:179] op_sel_hi:[1,0]
	v_pk_mul_f32 v[176:177], v[114:115], v[178:179] op_sel_hi:[1,0]
	v_exp_f32_e32 v170, v170
	v_exp_f32_e32 v171, v171
	v_exp_f32_e32 v172, v172
	v_exp_f32_e32 v173, v173
	v_exp_f32_e32 v174, v174
	v_exp_f32_e32 v175, v175
	v_exp_f32_e32 v176, v176
	v_exp_f32_e32 v177, v177
	v_pk_mul_f32 v[124:125], v[124:125], v[238:239] op_sel_hi:[1,0]
	v_pk_mul_f32 v[126:127], v[126:127], v[238:239] op_sel_hi:[1,0]
	v_pk_mul_f32 v[120:121], v[120:121], v[238:239] op_sel_hi:[1,0]
	v_pk_mul_f32 v[122:123], v[122:123], v[238:239] op_sel_hi:[1,0]
	v_pk_add_f32 v[170:171], v[170:171], v[180:181] op_sel_hi:[1,0]
	v_pk_add_f32 v[172:173], v[172:173], v[180:181] op_sel_hi:[1,0]
	v_pk_add_f32 v[174:175], v[174:175], v[180:181] op_sel_hi:[1,0]
	v_pk_add_f32 v[176:177], v[176:177], v[180:181] op_sel_hi:[1,0]
	v_rcp_f32_e32 v170, v170
	v_rcp_f32_e32 v171, v171
	v_rcp_f32_e32 v172, v172
	v_rcp_f32_e32 v173, v173
	v_rcp_f32_e32 v174, v174
	v_rcp_f32_e32 v175, v175
	v_rcp_f32_e32 v176, v176
	v_rcp_f32_e32 v177, v177
	v_pk_mul_f32 v[116:117], v[116:117], v[170:171]
	v_pk_mul_f32 v[118:119], v[118:119], v[172:173]
	v_pk_mul_f32 v[112:113], v[112:113], v[174:175]
	v_pk_mul_f32 v[114:115], v[114:115], v[176:177]
	v_pk_mul_f32 v[116:117], v[124:125], v[116:117]
	v_pk_mul_f32 v[118:119], v[126:127], v[118:119]
	v_pk_mul_f32 v[112:113], v[120:121], v[112:113]
	v_pk_mul_f32 v[114:115], v[122:123], v[114:115]
	v_cvt_pk_bf16_f32 v124, v116, v117
	v_cvt_pk_bf16_f32 v125, v118, v119
	v_cvt_pk_bf16_f32 v126, v112, v113
	v_cvt_pk_bf16_f32 v127, v114, v115
	global_store_dwordx4 v147, v[124:127], s[22:23]
	v_fmamk_f32 v240, v240, 0x3a800000, v153
	v_rsq_f32_e32 v240, v240
	v_add_u32_e32 v147, 0x16000, v146
	v_pk_mul_f32 v[104:105], v[104:105], v[240:241] op_sel_hi:[1,0]
	v_pk_mul_f32 v[106:107], v[106:107], v[240:241] op_sel_hi:[1,0]
	v_pk_mul_f32 v[96:97], v[96:97], v[240:241] op_sel_hi:[1,0]
	v_pk_mul_f32 v[98:99], v[98:99], v[240:241] op_sel_hi:[1,0]
	v_pk_mul_f32 v[170:171], v[104:105], v[178:179] op_sel_hi:[1,0]
	v_pk_mul_f32 v[172:173], v[106:107], v[178:179] op_sel_hi:[1,0]
	v_pk_mul_f32 v[174:175], v[96:97], v[178:179] op_sel_hi:[1,0]
	v_pk_mul_f32 v[176:177], v[98:99], v[178:179] op_sel_hi:[1,0]
	v_exp_f32_e32 v170, v170
	v_exp_f32_e32 v171, v171
	v_exp_f32_e32 v172, v172
	v_exp_f32_e32 v173, v173
	v_exp_f32_e32 v174, v174
	v_exp_f32_e32 v175, v175
	v_exp_f32_e32 v176, v176
	v_exp_f32_e32 v177, v177
	v_pk_mul_f32 v[108:109], v[108:109], v[240:241] op_sel_hi:[1,0]
	v_pk_mul_f32 v[110:111], v[110:111], v[240:241] op_sel_hi:[1,0]
	v_pk_mul_f32 v[100:101], v[100:101], v[240:241] op_sel_hi:[1,0]
	v_pk_mul_f32 v[102:103], v[102:103], v[240:241] op_sel_hi:[1,0]
	v_pk_add_f32 v[170:171], v[170:171], v[180:181] op_sel_hi:[1,0]
	v_pk_add_f32 v[172:173], v[172:173], v[180:181] op_sel_hi:[1,0]
	v_pk_add_f32 v[174:175], v[174:175], v[180:181] op_sel_hi:[1,0]
	v_pk_add_f32 v[176:177], v[176:177], v[180:181] op_sel_hi:[1,0]
	v_rcp_f32_e32 v170, v170
	v_rcp_f32_e32 v171, v171
	v_rcp_f32_e32 v172, v172
	v_rcp_f32_e32 v173, v173
	v_rcp_f32_e32 v174, v174
	v_rcp_f32_e32 v175, v175
	v_rcp_f32_e32 v176, v176
	v_rcp_f32_e32 v177, v177
	v_pk_mul_f32 v[104:105], v[104:105], v[170:171]
	v_pk_mul_f32 v[106:107], v[106:107], v[172:173]
	v_pk_mul_f32 v[96:97], v[96:97], v[174:175]
	v_pk_mul_f32 v[98:99], v[98:99], v[176:177]
	v_pk_mul_f32 v[104:105], v[108:109], v[104:105]
	v_pk_mul_f32 v[106:107], v[110:111], v[106:107]
	v_pk_mul_f32 v[96:97], v[100:101], v[96:97]
	v_pk_mul_f32 v[98:99], v[102:103], v[98:99]
	v_cvt_pk_bf16_f32 v108, v104, v105
	v_cvt_pk_bf16_f32 v109, v106, v107
	v_cvt_pk_bf16_f32 v110, v96, v97
	v_cvt_pk_bf16_f32 v111, v98, v99
	global_store_dwordx4 v147, v[108:111], s[22:23]
	v_fmamk_f32 v242, v242, 0x3a800000, v153
	v_rsq_f32_e32 v242, v242
	v_add_u32_e32 v147, 0x2c000, v146
	v_pk_mul_f32 v[88:89], v[88:89], v[242:243] op_sel_hi:[1,0]
	v_pk_mul_f32 v[90:91], v[90:91], v[242:243] op_sel_hi:[1,0]
	v_pk_mul_f32 v[80:81], v[80:81], v[242:243] op_sel_hi:[1,0]
	v_pk_mul_f32 v[82:83], v[82:83], v[242:243] op_sel_hi:[1,0]
	v_pk_mul_f32 v[170:171], v[88:89], v[178:179] op_sel_hi:[1,0]
	v_pk_mul_f32 v[172:173], v[90:91], v[178:179] op_sel_hi:[1,0]
	v_pk_mul_f32 v[174:175], v[80:81], v[178:179] op_sel_hi:[1,0]
	v_pk_mul_f32 v[176:177], v[82:83], v[178:179] op_sel_hi:[1,0]
	v_exp_f32_e32 v170, v170
	v_exp_f32_e32 v171, v171
	v_exp_f32_e32 v172, v172
	v_exp_f32_e32 v173, v173
	v_exp_f32_e32 v174, v174
	v_exp_f32_e32 v175, v175
	v_exp_f32_e32 v176, v176
	v_exp_f32_e32 v177, v177
	v_pk_mul_f32 v[92:93], v[92:93], v[242:243] op_sel_hi:[1,0]
	v_pk_mul_f32 v[94:95], v[94:95], v[242:243] op_sel_hi:[1,0]
	v_pk_mul_f32 v[84:85], v[84:85], v[242:243] op_sel_hi:[1,0]
	v_pk_mul_f32 v[86:87], v[86:87], v[242:243] op_sel_hi:[1,0]
	v_pk_add_f32 v[170:171], v[170:171], v[180:181] op_sel_hi:[1,0]
; __device__ __forceinline__ u32x4 pack8(f32x4 a, f32x4 b) { u32x4 w; w.x = cvt_pk_bf16(a[0], a[1]); w.y = cvt_pk_bf16(a[2], a[3]); w.z = cvt_pk_bf16(b[0], b[1]); w.w = cvt_pk_bf16(b[2], b[3]); return w; }
; __device__ __forceinline__ float sigm(float x) { return __builtin_amdgcn_rcpf(1.0f + __builtin_amdgcn_exp2f(-x * LOG2E)); }
; __device__ __forceinline__ bf16x8 pack8(const f32x16& p, int b) { u32x4 w; w.x = cvtpk(p[b], p[b + 1]); w.y = cvtpk(p[b + 2], p[b + 3]); w.z = cvtpk(p[b + 4], p[b + 5]); w.w = cvtpk(p[b + 6], p[b + 7]); return __builtin_bit_cast(bf16x8, w); }
;     __device__ __forceinline__ void operator()(const f32x4 (&acc)[2][2][4][2], const Unit& u, int wr, int wc, int fr, int fq) const {
;     ...
;             for (int m = 0; m < 4; ++m) {
;                 const int row = u.pm * BM + ai * HALF + wr * 64 + m * 16 + fr;
;                 const float rs = __builtin_amdgcn_rsqf(ssq[row] * (1.0f / 1024.0f) + EPS);
;                 f32x4 o[2];
; #pragma unroll
;                 for (int n = 0; n < 2; ++n)
; #pragma unroll
;                     for (int i = 0; i < 4; ++i) { const float g = acc[ai][0][m][n][i] * rs, up = acc[ai][1][m][n][i] * rs; o[n][i] = g * sigm(g) * up; }
;                 *(u32x4*)(h + (size_t)row * DFF + u.pn * HALF + wc * 32 + 8 * fq) = pack8(o[0], o[1]);
	v_pk_add_f32 v[172:173], v[172:173], v[180:181] op_sel_hi:[1,0]
	v_pk_add_f32 v[174:175], v[174:175], v[180:181] op_sel_hi:[1,0]
	v_pk_add_f32 v[176:177], v[176:177], v[180:181] op_sel_hi:[1,0]
	v_rcp_f32_e32 v170, v170
	v_rcp_f32_e32 v171, v171
	v_rcp_f32_e32 v172, v172
	v_rcp_f32_e32 v173, v173
	v_rcp_f32_e32 v174, v174
	v_rcp_f32_e32 v175, v175
	v_rcp_f32_e32 v176, v176
	v_rcp_f32_e32 v177, v177
	v_pk_mul_f32 v[88:89], v[88:89], v[170:171]
	v_pk_mul_f32 v[90:91], v[90:91], v[172:173]
	v_pk_mul_f32 v[80:81], v[80:81], v[174:175]
	v_pk_mul_f32 v[82:83], v[82:83], v[176:177]
	v_pk_mul_f32 v[88:89], v[92:93], v[88:89]
	v_pk_mul_f32 v[90:91], v[94:95], v[90:91]
	v_pk_mul_f32 v[80:81], v[84:85], v[80:81]
	v_pk_mul_f32 v[82:83], v[86:87], v[82:83]
	v_cvt_pk_bf16_f32 v92, v88, v89
	v_cvt_pk_bf16_f32 v93, v90, v91
	v_cvt_pk_bf16_f32 v94, v80, v81
	v_cvt_pk_bf16_f32 v95, v82, v83
	global_store_dwordx4 v147, v[92:95], s[22:23]
	v_fmamk_f32 v244, v244, 0x3a800000, v153
	v_rsq_f32_e32 v244, v244
	v_add_u32_e32 v147, 0x42000, v146
	v_pk_mul_f32 v[72:73], v[72:73], v[244:245] op_sel_hi:[1,0]
	v_pk_mul_f32 v[74:75], v[74:75], v[244:245] op_sel_hi:[1,0]
	v_pk_mul_f32 v[64:65], v[64:65], v[244:245] op_sel_hi:[1,0]
	v_pk_mul_f32 v[66:67], v[66:67], v[244:245] op_sel_hi:[1,0]
	v_pk_mul_f32 v[170:171], v[72:73], v[178:179] op_sel_hi:[1,0]
	v_pk_mul_f32 v[172:173], v[74:75], v[178:179] op_sel_hi:[1,0]
	v_pk_mul_f32 v[174:175], v[64:65], v[178:179] op_sel_hi:[1,0]
	v_pk_mul_f32 v[176:177], v[66:67], v[178:179] op_sel_hi:[1,0]
	v_exp_f32_e32 v170, v170
	v_exp_f32_e32 v171, v171
	v_exp_f32_e32 v172, v172
	v_exp_f32_e32 v173, v173
	v_exp_f32_e32 v174, v174
	v_exp_f32_e32 v175, v175
	v_exp_f32_e32 v176, v176
	v_exp_f32_e32 v177, v177
	v_pk_mul_f32 v[76:77], v[76:77], v[244:245] op_sel_hi:[1,0]
	v_pk_mul_f32 v[78:79], v[78:79], v[244:245] op_sel_hi:[1,0]
	v_pk_mul_f32 v[68:69], v[68:69], v[244:245] op_sel_hi:[1,0]
	v_pk_mul_f32 v[70:71], v[70:71], v[244:245] op_sel_hi:[1,0]
	v_pk_add_f32 v[170:171], v[170:171], v[180:181] op_sel_hi:[1,0]
	v_pk_add_f32 v[172:173], v[172:173], v[180:181] op_sel_hi:[1,0]
	v_pk_add_f32 v[174:175], v[174:175], v[180:181] op_sel_hi:[1,0]
	v_pk_add_f32 v[176:177], v[176:177], v[180:181] op_sel_hi:[1,0]
	v_rcp_f32_e32 v170, v170
	v_rcp_f32_e32 v171, v171
	v_rcp_f32_e32 v172, v172
	v_rcp_f32_e32 v173, v173
	v_rcp_f32_e32 v174, v174
	v_rcp_f32_e32 v175, v175
	v_rcp_f32_e32 v176, v176
	v_rcp_f32_e32 v177, v177
	v_pk_mul_f32 v[72:73], v[72:73], v[170:171]
	v_pk_mul_f32 v[74:75], v[74:75], v[172:173]
	v_pk_mul_f32 v[64:65], v[64:65], v[174:175]
	v_pk_mul_f32 v[66:67], v[66:67], v[176:177]
	v_pk_mul_f32 v[72:73], v[76:77], v[72:73]
	v_pk_mul_f32 v[74:75], v[78:79], v[74:75]
	v_pk_mul_f32 v[64:65], v[68:69], v[64:65]
	v_pk_mul_f32 v[66:67], v[70:71], v[66:67]
	v_cvt_pk_bf16_f32 v76, v72, v73
	v_cvt_pk_bf16_f32 v77, v74, v75
	v_cvt_pk_bf16_f32 v78, v64, v65
	v_cvt_pk_bf16_f32 v79, v66, v67
	global_store_dwordx4 v147, v[76:79], s[22:23]
	v_fmamk_f32 v246, v246, 0x3a800000, v153
	v_rsq_f32_e32 v246, v246
	v_add_u32_e32 v147, 0xb0000, v146
	v_pk_mul_f32 v[56:57], v[56:57], v[246:247] op_sel_hi:[1,0]
	v_pk_mul_f32 v[58:59], v[58:59], v[246:247] op_sel_hi:[1,0]
	v_pk_mul_f32 v[48:49], v[48:49], v[246:247] op_sel_hi:[1,0]
	v_pk_mul_f32 v[50:51], v[50:51], v[246:247] op_sel_hi:[1,0]
	v_pk_mul_f32 v[170:171], v[56:57], v[178:179] op_sel_hi:[1,0]
	v_pk_mul_f32 v[172:173], v[58:59], v[178:179] op_sel_hi:[1,0]
	v_pk_mul_f32 v[174:175], v[48:49], v[178:179] op_sel_hi:[1,0]
	v_pk_mul_f32 v[176:177], v[50:51], v[178:179] op_sel_hi:[1,0]
	v_exp_f32_e32 v170, v170
	v_exp_f32_e32 v171, v171
	v_exp_f32_e32 v172, v172
	v_exp_f32_e32 v173, v173
	v_exp_f32_e32 v174, v174
	v_exp_f32_e32 v175, v175
	v_exp_f32_e32 v176, v176
	v_exp_f32_e32 v177, v177
	v_pk_mul_f32 v[60:61], v[60:61], v[246:247] op_sel_hi:[1,0]
	v_pk_mul_f32 v[62:63], v[62:63], v[246:247] op_sel_hi:[1,0]
	v_pk_mul_f32 v[52:53], v[52:53], v[246:247] op_sel_hi:[1,0]
	v_pk_mul_f32 v[54:55], v[54:55], v[246:247] op_sel_hi:[1,0]
	v_pk_add_f32 v[170:171], v[170:171], v[180:181] op_sel_hi:[1,0]
	v_pk_add_f32 v[172:173], v[172:173], v[180:181] op_sel_hi:[1,0]
	v_pk_add_f32 v[174:175], v[174:175], v[180:181] op_sel_hi:[1,0]
	v_pk_add_f32 v[176:177], v[176:177], v[180:181] op_sel_hi:[1,0]
	v_rcp_f32_e32 v170, v170
	v_rcp_f32_e32 v171, v171
	v_rcp_f32_e32 v172, v172
	v_rcp_f32_e32 v173, v173
	v_rcp_f32_e32 v174, v174
	v_rcp_f32_e32 v175, v175
	v_rcp_f32_e32 v176, v176
	v_rcp_f32_e32 v177, v177
	v_pk_mul_f32 v[56:57], v[56:57], v[170:171]
	v_pk_mul_f32 v[58:59], v[58:59], v[172:173]
	v_pk_mul_f32 v[48:49], v[48:49], v[174:175]
	v_pk_mul_f32 v[50:51], v[50:51], v[176:177]
	v_pk_mul_f32 v[56:57], v[60:61], v[56:57]
	v_pk_mul_f32 v[58:59], v[62:63], v[58:59]
	v_pk_mul_f32 v[48:49], v[52:53], v[48:49]
	v_pk_mul_f32 v[50:51], v[54:55], v[50:51]
	v_cvt_pk_bf16_f32 v60, v56, v57
	v_cvt_pk_bf16_f32 v61, v58, v59
	v_cvt_pk_bf16_f32 v62, v48, v49
	v_cvt_pk_bf16_f32 v63, v50, v51
	global_store_dwordx4 v147, v[60:63], s[22:23]
	v_fmamk_f32 v248, v248, 0x3a800000, v153
	v_rsq_f32_e32 v248, v248
	v_add_u32_e32 v147, 0xc6000, v146
	v_pk_mul_f32 v[40:41], v[40:41], v[248:249] op_sel_hi:[1,0]
	v_pk_mul_f32 v[42:43], v[42:43], v[248:249] op_sel_hi:[1,0]
	v_pk_mul_f32 v[32:33], v[32:33], v[248:249] op_sel_hi:[1,0]
	v_pk_mul_f32 v[34:35], v[34:35], v[248:249] op_sel_hi:[1,0]
	v_pk_mul_f32 v[170:171], v[40:41], v[178:179] op_sel_hi:[1,0]
	v_pk_mul_f32 v[172:173], v[42:43], v[178:179] op_sel_hi:[1,0]
	v_pk_mul_f32 v[174:175], v[32:33], v[178:179] op_sel_hi:[1,0]
	v_pk_mul_f32 v[176:177], v[34:35], v[178:179] op_sel_hi:[1,0]
; __device__ __forceinline__ u32x4 pack8(f32x4 a, f32x4 b) { u32x4 w; w.x = cvt_pk_bf16(a[0], a[1]); w.y = cvt_pk_bf16(a[2], a[3]); w.z = cvt_pk_bf16(b[0], b[1]); w.w = cvt_pk_bf16(b[2], b[3]); return w; }
; __device__ __forceinline__ float sigm(float x) { return __builtin_amdgcn_rcpf(1.0f + __builtin_amdgcn_exp2f(-x * LOG2E)); }
; __device__ __forceinline__ bf16x8 pack8(const f32x16& p, int b) { u32x4 w; w.x = cvtpk(p[b], p[b + 1]); w.y = cvtpk(p[b + 2], p[b + 3]); w.z = cvtpk(p[b + 4], p[b + 5]); w.w = cvtpk(p[b + 6], p[b + 7]); return __builtin_bit_cast(bf16x8, w); }
;     __device__ __forceinline__ void operator()(const f32x4 (&acc)[2][2][4][2], const Unit& u, int wr, int wc, int fr, int fq) const {
;     ...
;             for (int m = 0; m < 4; ++m) {
;                 const int row = u.pm * BM + ai * HALF + wr * 64 + m * 16 + fr;
;                 const float rs = __builtin_amdgcn_rsqf(ssq[row] * (1.0f / 1024.0f) + EPS);
;                 f32x4 o[2];
; #pragma unroll
;                 for (int n = 0; n < 2; ++n)
; #pragma unroll
;                     for (int i = 0; i < 4; ++i) { const float g = acc[ai][0][m][n][i] * rs, up = acc[ai][1][m][n][i] * rs; o[n][i] = g * sigm(g) * up; }
;                 *(u32x4*)(h + (size_t)row * DFF + u.pn * HALF + wc * 32 + 8 * fq) = pack8(o[0], o[1]);
	v_exp_f32_e32 v170, v170
	v_exp_f32_e32 v171, v171
	v_exp_f32_e32 v172, v172
	v_exp_f32_e32 v173, v173
	v_exp_f32_e32 v174, v174
	v_exp_f32_e32 v175, v175
	v_exp_f32_e32 v176, v176
	v_exp_f32_e32 v177, v177
	v_pk_mul_f32 v[44:45], v[44:45], v[248:249] op_sel_hi:[1,0]
	v_pk_mul_f32 v[46:47], v[46:47], v[248:249] op_sel_hi:[1,0]
	v_pk_mul_f32 v[36:37], v[36:37], v[248:249] op_sel_hi:[1,0]
	v_pk_mul_f32 v[38:39], v[38:39], v[248:249] op_sel_hi:[1,0]
	v_pk_add_f32 v[170:171], v[170:171], v[180:181] op_sel_hi:[1,0]
	v_pk_add_f32 v[172:173], v[172:173], v[180:181] op_sel_hi:[1,0]
	v_pk_add_f32 v[174:175], v[174:175], v[180:181] op_sel_hi:[1,0]
	v_pk_add_f32 v[176:177], v[176:177], v[180:181] op_sel_hi:[1,0]
	v_rcp_f32_e32 v170, v170
	v_rcp_f32_e32 v171, v171
	v_rcp_f32_e32 v172, v172
	v_rcp_f32_e32 v173, v173
	v_rcp_f32_e32 v174, v174
	v_rcp_f32_e32 v175, v175
	v_rcp_f32_e32 v176, v176
	v_rcp_f32_e32 v177, v177
	v_pk_mul_f32 v[40:41], v[40:41], v[170:171]
	v_pk_mul_f32 v[42:43], v[42:43], v[172:173]
	v_pk_mul_f32 v[32:33], v[32:33], v[174:175]
	v_pk_mul_f32 v[34:35], v[34:35], v[176:177]
	v_pk_mul_f32 v[40:41], v[44:45], v[40:41]
	v_pk_mul_f32 v[42:43], v[46:47], v[42:43]
	v_pk_mul_f32 v[32:33], v[36:37], v[32:33]
	v_pk_mul_f32 v[34:35], v[38:39], v[34:35]
	v_cvt_pk_bf16_f32 v44, v40, v41
	v_cvt_pk_bf16_f32 v45, v42, v43
	v_cvt_pk_bf16_f32 v46, v32, v33
	v_cvt_pk_bf16_f32 v47, v34, v35
	global_store_dwordx4 v147, v[44:47], s[22:23]
	v_fmamk_f32 v250, v250, 0x3a800000, v153
	v_rsq_f32_e32 v250, v250
	v_add_u32_e32 v147, 0xdc000, v146
	v_pk_mul_f32 v[24:25], v[24:25], v[250:251] op_sel_hi:[1,0]
	v_pk_mul_f32 v[26:27], v[26:27], v[250:251] op_sel_hi:[1,0]
	v_pk_mul_f32 v[16:17], v[16:17], v[250:251] op_sel_hi:[1,0]
	v_pk_mul_f32 v[18:19], v[18:19], v[250:251] op_sel_hi:[1,0]
	v_pk_mul_f32 v[170:171], v[24:25], v[178:179] op_sel_hi:[1,0]
	v_pk_mul_f32 v[172:173], v[26:27], v[178:179] op_sel_hi:[1,0]
	v_pk_mul_f32 v[174:175], v[16:17], v[178:179] op_sel_hi:[1,0]
	v_pk_mul_f32 v[176:177], v[18:19], v[178:179] op_sel_hi:[1,0]
	v_exp_f32_e32 v170, v170
	v_exp_f32_e32 v171, v171
	v_exp_f32_e32 v172, v172
	v_exp_f32_e32 v173, v173
	v_exp_f32_e32 v174, v174
	v_exp_f32_e32 v175, v175
	v_exp_f32_e32 v176, v176
	v_exp_f32_e32 v177, v177
	v_pk_mul_f32 v[28:29], v[28:29], v[250:251] op_sel_hi:[1,0]
	v_pk_mul_f32 v[30:31], v[30:31], v[250:251] op_sel_hi:[1,0]
	v_pk_mul_f32 v[20:21], v[20:21], v[250:251] op_sel_hi:[1,0]
	v_pk_mul_f32 v[22:23], v[22:23], v[250:251] op_sel_hi:[1,0]
	v_pk_add_f32 v[170:171], v[170:171], v[180:181] op_sel_hi:[1,0]
	v_pk_add_f32 v[172:173], v[172:173], v[180:181] op_sel_hi:[1,0]
	v_pk_add_f32 v[174:175], v[174:175], v[180:181] op_sel_hi:[1,0]
	v_pk_add_f32 v[176:177], v[176:177], v[180:181] op_sel_hi:[1,0]
	v_rcp_f32_e32 v170, v170
	v_rcp_f32_e32 v171, v171
	v_rcp_f32_e32 v172, v172
	v_rcp_f32_e32 v173, v173
	v_rcp_f32_e32 v174, v174
	v_rcp_f32_e32 v175, v175
	v_rcp_f32_e32 v176, v176
	v_rcp_f32_e32 v177, v177
	v_pk_mul_f32 v[24:25], v[24:25], v[170:171]
	v_pk_mul_f32 v[26:27], v[26:27], v[172:173]
	v_pk_mul_f32 v[16:17], v[16:17], v[174:175]
	v_pk_mul_f32 v[18:19], v[18:19], v[176:177]
	v_pk_mul_f32 v[24:25], v[28:29], v[24:25]
	v_pk_mul_f32 v[26:27], v[30:31], v[26:27]
	v_pk_mul_f32 v[16:17], v[20:21], v[16:17]
	v_pk_mul_f32 v[18:19], v[22:23], v[18:19]
	v_cvt_pk_bf16_f32 v28, v24, v25
	v_cvt_pk_bf16_f32 v29, v26, v27
	v_cvt_pk_bf16_f32 v30, v16, v17
	v_cvt_pk_bf16_f32 v31, v18, v19
	global_store_dwordx4 v147, v[28:31], s[22:23]
	v_fmamk_f32 v252, v252, 0x3a800000, v153
	v_rsq_f32_e32 v252, v252
	v_add_u32_e32 v147, 0xf2000, v146
	v_pk_mul_f32 v[8:9], v[8:9], v[252:253] op_sel_hi:[1,0]
	v_pk_mul_f32 v[10:11], v[10:11], v[252:253] op_sel_hi:[1,0]
	v_pk_mul_f32 v[0:1], v[0:1], v[252:253] op_sel_hi:[1,0]
	v_pk_mul_f32 v[2:3], v[2:3], v[252:253] op_sel_hi:[1,0]
	v_pk_mul_f32 v[170:171], v[8:9], v[178:179] op_sel_hi:[1,0]
	v_pk_mul_f32 v[172:173], v[10:11], v[178:179] op_sel_hi:[1,0]
	v_pk_mul_f32 v[174:175], v[0:1], v[178:179] op_sel_hi:[1,0]
	v_pk_mul_f32 v[176:177], v[2:3], v[178:179] op_sel_hi:[1,0]
	v_exp_f32_e32 v170, v170
	v_exp_f32_e32 v171, v171
	v_exp_f32_e32 v172, v172
	v_exp_f32_e32 v173, v173
	v_exp_f32_e32 v174, v174
	v_exp_f32_e32 v175, v175
	v_exp_f32_e32 v176, v176
	v_exp_f32_e32 v177, v177
	v_pk_mul_f32 v[12:13], v[12:13], v[252:253] op_sel_hi:[1,0]
	v_pk_mul_f32 v[14:15], v[14:15], v[252:253] op_sel_hi:[1,0]
	v_pk_mul_f32 v[4:5], v[4:5], v[252:253] op_sel_hi:[1,0]
	v_pk_mul_f32 v[6:7], v[6:7], v[252:253] op_sel_hi:[1,0]
	v_pk_add_f32 v[170:171], v[170:171], v[180:181] op_sel_hi:[1,0]
	v_pk_add_f32 v[172:173], v[172:173], v[180:181] op_sel_hi:[1,0]
	v_pk_add_f32 v[174:175], v[174:175], v[180:181] op_sel_hi:[1,0]
	v_pk_add_f32 v[176:177], v[176:177], v[180:181] op_sel_hi:[1,0]
	v_rcp_f32_e32 v170, v170
	v_rcp_f32_e32 v171, v171
	v_rcp_f32_e32 v172, v172
	v_rcp_f32_e32 v173, v173
	v_rcp_f32_e32 v174, v174
	v_rcp_f32_e32 v175, v175
	v_rcp_f32_e32 v176, v176
	v_rcp_f32_e32 v177, v177
	v_pk_mul_f32 v[8:9], v[8:9], v[170:171]
	v_pk_mul_f32 v[10:11], v[10:11], v[172:173]
	v_pk_mul_f32 v[0:1], v[0:1], v[174:175]
	v_pk_mul_f32 v[2:3], v[2:3], v[176:177]
	v_pk_mul_f32 v[8:9], v[12:13], v[8:9]
	v_pk_mul_f32 v[10:11], v[14:15], v[10:11]
	v_pk_mul_f32 v[0:1], v[4:5], v[0:1]
	v_pk_mul_f32 v[2:3], v[6:7], v[2:3]
	v_cvt_pk_bf16_f32 v12, v8, v9
	v_cvt_pk_bf16_f32 v13, v10, v11
	v_cvt_pk_bf16_f32 v14, v0, v1
	v_cvt_pk_bf16_f32 v15, v2, v3
	global_store_dwordx4 v147, v[12:15], s[22:23]
	s_cbranch_vccnz .LBB0_704
	s_andn2_b64 vcc, exec, s[8:9]
	s_cbranch_vccnz .LBB0_703
	s_barrier
	s_branch .LBB0_703

;     __device__ __forceinline__ void operator()(const f32x4 (&acc)[2][2][4][2], const Unit& u, int wr, int wc, int fr, int fq) const {
;     ...
;                 const int row = u.pm * BM + ai * HALF + wr * 64 + m * 16 + fr;
;                 const float rs = __builtin_amdgcn_rsqf(ssq[row] * (1.0f / 1024.0f) + EPS);
; template <class Epi, class Sched, bool ALIGN_EPI = false, bool SP2 = false>
; __device__ __forceinline__ void gemm_phase(PG8_LAS unsigned char* lds, const Gemm g, const Sched& S, const Epi& E) {
;     ...
;         for (int a = 0; a < 2; ++a)
; #pragma unroll
;             for (int b = 0; b < 2; ++b)
; #pragma unroll
;                 for (int m = 0; m < 4; ++m)
; #pragma unroll
;                     for (int n = 0; n < 2; ++n) acc[a][b][m][n] = (f32x4){0.f, 0.f, 0.f, 0.f};
;         cur = nxt; cA = nA; cB = nB; ++ui;
.LBB0_1165:
	s_ashr_i32 s19, s18, 31
	s_lshl_b64 s[20:21], s[18:19], 19
	s_add_u32 s20, s88, s20
	s_addc_u32 s21, s89, s21
	s_and_b64 s[24:25], s[6:7], exec
	s_cselect_b32 s3, s21, s27
	s_cselect_b32 s19, s20, s26
	s_ashr_i32 s17, s16, 31
	s_lshl_b64 s[24:25], s[16:17], 19
	s_add_u32 s24, s33, s24
	s_addc_u32 s25, s34, s25
	s_and_b64 s[30:31], s[6:7], exec
	s_cselect_b32 s17, s25, s29
	s_cselect_b32 s23, s24, s28
	s_add_u32 s26, s26, 0x40080
	s_addc_u32 s27, s27, 0
	s_add_u32 s49, s28, 0x100
	v_mov_b32_e32 v4, 0
	s_addc_u32 s50, s29, 0
	s_mov_b32 s51, -2
	v_mov_b32_e32 v5, v4
	v_mov_b32_e32 v6, v4
	v_mov_b32_e32 v7, v4
	v_mov_b32_e32 v12, v4
	v_mov_b32_e32 v13, v4
	v_mov_b32_e32 v14, v4
	v_mov_b32_e32 v15, v4
	v_mov_b32_e32 v20, v4
	v_mov_b32_e32 v21, v4
	v_mov_b32_e32 v22, v4
	v_mov_b32_e32 v23, v4
	s_waitcnt vmcnt(0)
	v_mov_b32_e32 v28, v4
	v_mov_b32_e32 v29, v4
	v_mov_b32_e32 v30, v4
	v_mov_b32_e32 v31, v4
	v_mov_b32_e32 v36, v4
	v_mov_b32_e32 v37, v4
	v_mov_b32_e32 v38, v4
	v_mov_b32_e32 v39, v4
	v_mov_b32_e32 v44, v4
	v_mov_b32_e32 v45, v4
	v_mov_b32_e32 v46, v4
	v_mov_b32_e32 v47, v4
	v_mov_b32_e32 v52, v4
	v_mov_b32_e32 v53, v4
	v_mov_b32_e32 v54, v4
	v_mov_b32_e32 v55, v4
	v_mov_b32_e32 v60, v4
	v_mov_b32_e32 v61, v4
	v_mov_b32_e32 v62, v4
	v_mov_b32_e32 v63, v4
	v_mov_b32_e32 v0, v4
	v_mov_b32_e32 v1, v4
	v_mov_b32_e32 v2, v4
	v_mov_b32_e32 v3, v4
	v_mov_b32_e32 v8, v4
	v_mov_b32_e32 v9, v4
	v_mov_b32_e32 v10, v4
	v_mov_b32_e32 v11, v4
	v_mov_b32_e32 v16, v4
	v_mov_b32_e32 v17, v4
	v_mov_b32_e32 v18, v4
	v_mov_b32_e32 v19, v4
	v_mov_b32_e32 v24, v4
	v_mov_b32_e32 v25, v4
	v_mov_b32_e32 v26, v4
	v_mov_b32_e32 v27, v4
	v_mov_b32_e32 v32, v4
	v_mov_b32_e32 v33, v4
	v_mov_b32_e32 v34, v4
	v_mov_b32_e32 v35, v4
	v_mov_b32_e32 v40, v4
	v_mov_b32_e32 v41, v4
	v_mov_b32_e32 v42, v4
	v_mov_b32_e32 v43, v4
	v_mov_b32_e32 v48, v4
	v_mov_b32_e32 v49, v4
	v_mov_b32_e32 v50, v4
	v_mov_b32_e32 v51, v4
	v_mov_b32_e32 v56, v4
	v_mov_b32_e32 v57, v4
	v_mov_b32_e32 v58, v4
	v_mov_b32_e32 v59, v4
	v_mov_b32_e32 v68, v4
	v_mov_b32_e32 v69, v4
	v_mov_b32_e32 v70, v4
	v_mov_b32_e32 v71, v4
	v_mov_b32_e32 v76, v4
	v_mov_b32_e32 v77, v4
	v_mov_b32_e32 v78, v4
	v_mov_b32_e32 v79, v4
	v_mov_b32_e32 v84, v4
	v_mov_b32_e32 v85, v4
	v_mov_b32_e32 v86, v4
	v_mov_b32_e32 v87, v4
	v_mov_b32_e32 v92, v4
	v_mov_b32_e32 v93, v4
	v_mov_b32_e32 v94, v4
	v_mov_b32_e32 v95, v4
	v_mov_b32_e32 v100, v4
	v_mov_b32_e32 v101, v4
	v_mov_b32_e32 v102, v4
	v_mov_b32_e32 v103, v4
	v_mov_b32_e32 v108, v4
	v_mov_b32_e32 v109, v4
	v_mov_b32_e32 v110, v4
	v_mov_b32_e32 v111, v4
	v_mov_b32_e32 v120, v4
	v_mov_b32_e32 v121, v4
	v_mov_b32_e32 v122, v4
	v_mov_b32_e32 v123, v4
	v_mov_b32_e32 v124, v4
	v_mov_b32_e32 v125, v4
	v_mov_b32_e32 v126, v4
	v_mov_b32_e32 v127, v4
	v_mov_b32_e32 v64, v4
	v_mov_b32_e32 v65, v4
	v_mov_b32_e32 v66, v4
	v_mov_b32_e32 v67, v4
	v_mov_b32_e32 v72, v4
	v_mov_b32_e32 v73, v4
	v_mov_b32_e32 v74, v4
	v_mov_b32_e32 v75, v4
	v_mov_b32_e32 v80, v4
	v_mov_b32_e32 v81, v4
	v_mov_b32_e32 v82, v4
	v_mov_b32_e32 v83, v4
	v_mov_b32_e32 v88, v4
	v_mov_b32_e32 v89, v4
	v_mov_b32_e32 v90, v4
	v_mov_b32_e32 v91, v4
	v_mov_b32_e32 v96, v4
	v_mov_b32_e32 v97, v4
	v_mov_b32_e32 v98, v4
	v_mov_b32_e32 v99, v4
	v_mov_b32_e32 v104, v4
	v_mov_b32_e32 v105, v4
	v_mov_b32_e32 v106, v4
	v_mov_b32_e32 v107, v4
	v_mov_b32_e32 v112, v4
	v_mov_b32_e32 v113, v4
	v_mov_b32_e32 v114, v4
	v_mov_b32_e32 v115, v4
	v_mov_b32_e32 v116, v4
	v_mov_b32_e32 v117, v4
	v_mov_b32_e32 v118, v4
	v_mov_b32_e32 v119, v4
	v_lshl_add_u32 v146, s22, 8, v148
	v_lshlrev_b32_e32 v146, 2, v146
	global_load_dword v238, v146, s[0:1]
	global_load_dword v240, v146, s[0:1] offset:64
	global_load_dword v242, v146, s[0:1] offset:128
	global_load_dword v244, v146, s[0:1] offset:192
	global_load_dword v246, v146, s[0:1] offset:512
	global_load_dword v248, v146, s[0:1] offset:576
	global_load_dword v250, v146, s[0:1] offset:640
	global_load_dword v252, v146, s[0:1] offset:704

; __device__ __forceinline__ u32x4 pack8(f32x4 a, f32x4 b) { u32x4 w; w.x = cvt_pk_bf16(a[0], a[1]); w.y = cvt_pk_bf16(a[2], a[3]); w.z = cvt_pk_bf16(b[0], b[1]); w.w = cvt_pk_bf16(b[2], b[3]); return w; }
; __device__ __forceinline__ float sigm(float x) { return __builtin_amdgcn_rcpf(1.0f + __builtin_amdgcn_exp2f(-x * LOG2E)); }
; __device__ __forceinline__ bf16x8 pack8(const f32x16& p, int b) { u32x4 w; w.x = cvtpk(p[b], p[b + 1]); w.y = cvtpk(p[b + 2], p[b + 3]); w.z = cvtpk(p[b + 4], p[b + 5]); w.w = cvtpk(p[b + 6], p[b + 7]); return __builtin_bit_cast(bf16x8, w); }
;     __device__ __forceinline__ void operator()(const f32x4 (&acc)[2][2][4][2], const Unit& u, int wr, int wc, int fr, int fq) const {
;     ...
;             for (int m = 0; m < 4; ++m) {
;                 const int row = u.pm * BM + ai * HALF + wr * 64 + m * 16 + fr;
;                 const float rs = __builtin_amdgcn_rsqf(ssq[row] * (1.0f / 1024.0f) + EPS);
;                 f32x4 o[2];
; #pragma unroll
;                 for (int n = 0; n < 2; ++n)
; #pragma unroll
;                     for (int i = 0; i < 4; ++i) { const float g = acc[ai][0][m][n][i] * rs, up = acc[ai][1][m][n][i] * rs; o[n][i] = g * sigm(g) * up; }
;                 *(u32x4*)(h + (size_t)row * DFF + u.pn * HALF + wc * 32 + 8 * fq) = pack8(o[0], o[1]);
.LBB0_1169:
	v_lshl_add_u32 v146, s22, 8, v148
	s_lshl_b32 s22, s2, 8
	s_add_i32 s22, s22, s8
	s_add_u32 s22, s66, s22
	s_addc_u32 s23, s67, 0
	v_mad_u32_u24 v146, v146, s47, v136
	v_mov_b32_e32 v178, 0xbfb8aa3b
	v_mov_b32_e32 v180, 1.0
	s_andn2_b64 vcc, exec, s[6:7]
	s_mov_b64 s[6:7], -1
	s_waitcnt vmcnt(8)
	v_fmamk_f32 v238, v238, 0x3a800000, v153
	v_rsq_f32_e32 v238, v238
	v_mov_b32_e32 v147, v146
	v_pk_mul_f32 v[116:117], v[116:117], v[238:239] op_sel_hi:[1,0]
	v_pk_mul_f32 v[118:119], v[118:119], v[238:239] op_sel_hi:[1,0]
	v_pk_mul_f32 v[112:113], v[112:113], v[238:239] op_sel_hi:[1,0]
	v_pk_mul_f32 v[114:115], v[114:115], v[238:239] op_sel_hi:[1,0]
	v_pk_mul_f32 v[170:171], v[116:117], v[178:179] op_sel_hi:[1,0]
	v_pk_mul_f32 v[172:173], v[118:119], v[178:179] op_sel_hi:[1,0]
	v_pk_mul_f32 v[174:175], v[112:113], v[178:179] op_sel_hi:[1,0]
	v_pk_mul_f32 v[176:177], v[114:115], v[178:179] op_sel_hi:[1,0]
	v_exp_f32_e32 v170, v170
	v_exp_f32_e32 v171, v171
	v_exp_f32_e32 v172, v172
	v_exp_f32_e32 v173, v173
	v_exp_f32_e32 v174, v174
	v_exp_f32_e32 v175, v175
	v_exp_f32_e32 v176, v176
	v_exp_f32_e32 v177, v177
	v_pk_mul_f32 v[124:125], v[124:125], v[238:239] op_sel_hi:[1,0]
	v_pk_mul_f32 v[126:127], v[126:127], v[238:239] op_sel_hi:[1,0]
	v_pk_mul_f32 v[120:121], v[120:121], v[238:239] op_sel_hi:[1,0]
	v_pk_mul_f32 v[122:123], v[122:123], v[238:239] op_sel_hi:[1,0]
	v_pk_add_f32 v[170:171], v[170:171], v[180:181] op_sel_hi:[1,0]
	v_pk_add_f32 v[172:173], v[172:173], v[180:181] op_sel_hi:[1,0]
	v_pk_add_f32 v[174:175], v[174:175], v[180:181] op_sel_hi:[1,0]
	v_pk_add_f32 v[176:177], v[176:177], v[180:181] op_sel_hi:[1,0]
	v_rcp_f32_e32 v170, v170
	v_rcp_f32_e32 v171, v171
	v_rcp_f32_e32 v172, v172
	v_rcp_f32_e32 v173, v173
	v_rcp_f32_e32 v174, v174
	v_rcp_f32_e32 v175, v175
	v_rcp_f32_e32 v176, v176
	v_rcp_f32_e32 v177, v177
	v_pk_mul_f32 v[116:117], v[116:117], v[170:171]
	v_pk_mul_f32 v[118:119], v[118:119], v[172:173]
	v_pk_mul_f32 v[112:113], v[112:113], v[174:175]
	v_pk_mul_f32 v[114:115], v[114:115], v[176:177]
	v_pk_mul_f32 v[116:117], v[124:125], v[116:117]
	v_pk_mul_f32 v[118:119], v[126:127], v[118:119]
	v_pk_mul_f32 v[112:113], v[120:121], v[112:113]
	v_pk_mul_f32 v[114:115], v[122:123], v[114:115]
	v_cvt_pk_bf16_f32 v124, v116, v117
	v_cvt_pk_bf16_f32 v125, v118, v119
	v_cvt_pk_bf16_f32 v126, v112, v113
	v_cvt_pk_bf16_f32 v127, v114, v115
	global_store_dwordx4 v147, v[124:127], s[22:23]
	v_fmamk_f32 v240, v240, 0x3a800000, v153
	v_rsq_f32_e32 v240, v240
	v_add_u32_e32 v147, 0x16000, v146
	v_pk_mul_f32 v[104:105], v[104:105], v[240:241] op_sel_hi:[1,0]
	v_pk_mul_f32 v[106:107], v[106:107], v[240:241] op_sel_hi:[1,0]
	v_pk_mul_f32 v[96:97], v[96:97], v[240:241] op_sel_hi:[1,0]
	v_pk_mul_f32 v[98:99], v[98:99], v[240:241] op_sel_hi:[1,0]
	v_pk_mul_f32 v[170:171], v[104:105], v[178:179] op_sel_hi:[1,0]
	v_pk_mul_f32 v[172:173], v[106:107], v[178:179] op_sel_hi:[1,0]
	v_pk_mul_f32 v[174:175], v[96:97], v[178:179] op_sel_hi:[1,0]
	v_pk_mul_f32 v[176:177], v[98:99], v[178:179] op_sel_hi:[1,0]
	v_exp_f32_e32 v170, v170
	v_exp_f32_e32 v171, v171
	v_exp_f32_e32 v172, v172
	v_exp_f32_e32 v173, v173
	v_exp_f32_e32 v174, v174
	v_exp_f32_e32 v175, v175
	v_exp_f32_e32 v176, v176
	v_exp_f32_e32 v177, v177
	v_pk_mul_f32 v[108:109], v[108:109], v[240:241] op_sel_hi:[1,0]
	v_pk_mul_f32 v[110:111], v[110:111], v[240:241] op_sel_hi:[1,0]
	v_pk_mul_f32 v[100:101], v[100:101], v[240:241] op_sel_hi:[1,0]
	v_pk_mul_f32 v[102:103], v[102:103], v[240:241] op_sel_hi:[1,0]
	v_pk_add_f32 v[170:171], v[170:171], v[180:181] op_sel_hi:[1,0]
	v_pk_add_f32 v[172:173], v[172:173], v[180:181] op_sel_hi:[1,0]
	v_pk_add_f32 v[174:175], v[174:175], v[180:181] op_sel_hi:[1,0]
	v_pk_add_f32 v[176:177], v[176:177], v[180:181] op_sel_hi:[1,0]
	v_rcp_f32_e32 v170, v170
	v_rcp_f32_e32 v171, v171
	v_rcp_f32_e32 v172, v172
	v_rcp_f32_e32 v173, v173
	v_rcp_f32_e32 v174, v174
	v_rcp_f32_e32 v175, v175
	v_rcp_f32_e32 v176, v176
	v_rcp_f32_e32 v177, v177
	v_pk_mul_f32 v[104:105], v[104:105], v[170:171]
	v_pk_mul_f32 v[106:107], v[106:107], v[172:173]
	v_pk_mul_f32 v[96:97], v[96:97], v[174:175]
	v_pk_mul_f32 v[98:99], v[98:99], v[176:177]
	v_pk_mul_f32 v[104:105], v[108:109], v[104:105]
	v_pk_mul_f32 v[106:107], v[110:111], v[106:107]
	v_pk_mul_f32 v[96:97], v[100:101], v[96:97]
	v_pk_mul_f32 v[98:99], v[102:103], v[98:99]
	v_cvt_pk_bf16_f32 v108, v104, v105
	v_cvt_pk_bf16_f32 v109, v106, v107
	v_cvt_pk_bf16_f32 v110, v96, v97
	v_cvt_pk_bf16_f32 v111, v98, v99
	global_store_dwordx4 v147, v[108:111], s[22:23]
	v_fmamk_f32 v242, v242, 0x3a800000, v153
	v_rsq_f32_e32 v242, v242
	v_add_u32_e32 v147, 0x2c000, v146
	v_pk_mul_f32 v[88:89], v[88:89], v[242:243] op_sel_hi:[1,0]
	v_pk_mul_f32 v[90:91], v[90:91], v[242:243] op_sel_hi:[1,0]
	v_pk_mul_f32 v[80:81], v[80:81], v[242:243] op_sel_hi:[1,0]
	v_pk_mul_f32 v[82:83], v[82:83], v[242:243] op_sel_hi:[1,0]
	v_pk_mul_f32 v[170:171], v[88:89], v[178:179] op_sel_hi:[1,0]
	v_pk_mul_f32 v[172:173], v[90:91], v[178:179] op_sel_hi:[1,0]
	v_pk_mul_f32 v[174:175], v[80:81], v[178:179] op_sel_hi:[1,0]
	v_pk_mul_f32 v[176:177], v[82:83], v[178:179] op_sel_hi:[1,0]
	v_exp_f32_e32 v170, v170
	v_exp_f32_e32 v171, v171
	v_exp_f32_e32 v172, v172
	v_exp_f32_e32 v173, v173
	v_exp_f32_e32 v174, v174
	v_exp_f32_e32 v175, v175
	v_exp_f32_e32 v176, v176
	v_exp_f32_e32 v177, v177
	v_pk_mul_f32 v[92:93], v[92:93], v[242:243] op_sel_hi:[1,0]
	v_pk_mul_f32 v[94:95], v[94:95], v[242:243] op_sel_hi:[1,0]
	v_pk_mul_f32 v[84:85], v[84:85], v[242:243] op_sel_hi:[1,0]
	v_pk_mul_f32 v[86:87], v[86:87], v[242:243] op_sel_hi:[1,0]
; __device__ __forceinline__ u32x4 pack8(f32x4 a, f32x4 b) { u32x4 w; w.x = cvt_pk_bf16(a[0], a[1]); w.y = cvt_pk_bf16(a[2], a[3]); w.z = cvt_pk_bf16(b[0], b[1]); w.w = cvt_pk_bf16(b[2], b[3]); return w; }
; __device__ __forceinline__ float sigm(float x) { return __builtin_amdgcn_rcpf(1.0f + __builtin_amdgcn_exp2f(-x * LOG2E)); }
; __device__ __forceinline__ bf16x8 pack8(const f32x16& p, int b) { u32x4 w; w.x = cvtpk(p[b], p[b + 1]); w.y = cvtpk(p[b + 2], p[b + 3]); w.z = cvtpk(p[b + 4], p[b + 5]); w.w = cvtpk(p[b + 6], p[b + 7]); return __builtin_bit_cast(bf16x8, w); }
;     __device__ __forceinline__ void operator()(const f32x4 (&acc)[2][2][4][2], const Unit& u, int wr, int wc, int fr, int fq) const {
;     ...
;             for (int m = 0; m < 4; ++m) {
;                 const int row = u.pm * BM + ai * HALF + wr * 64 + m * 16 + fr;
;                 const float rs = __builtin_amdgcn_rsqf(ssq[row] * (1.0f / 1024.0f) + EPS);
;                 f32x4 o[2];
; #pragma unroll
;                 for (int n = 0; n < 2; ++n)
; #pragma unroll
;                     for (int i = 0; i < 4; ++i) { const float g = acc[ai][0][m][n][i] * rs, up = acc[ai][1][m][n][i] * rs; o[n][i] = g * sigm(g) * up; }
;                 *(u32x4*)(h + (size_t)row * DFF + u.pn * HALF + wc * 32 + 8 * fq) = pack8(o[0], o[1]);
	v_pk_add_f32 v[170:171], v[170:171], v[180:181] op_sel_hi:[1,0]
	v_pk_add_f32 v[172:173], v[172:173], v[180:181] op_sel_hi:[1,0]
	v_pk_add_f32 v[174:175], v[174:175], v[180:181] op_sel_hi:[1,0]
	v_pk_add_f32 v[176:177], v[176:177], v[180:181] op_sel_hi:[1,0]
	v_rcp_f32_e32 v170, v170
	v_rcp_f32_e32 v171, v171
	v_rcp_f32_e32 v172, v172
	v_rcp_f32_e32 v173, v173
	v_rcp_f32_e32 v174, v174
	v_rcp_f32_e32 v175, v175
	v_rcp_f32_e32 v176, v176
	v_rcp_f32_e32 v177, v177
	v_pk_mul_f32 v[88:89], v[88:89], v[170:171]
	v_pk_mul_f32 v[90:91], v[90:91], v[172:173]
	v_pk_mul_f32 v[80:81], v[80:81], v[174:175]
	v_pk_mul_f32 v[82:83], v[82:83], v[176:177]
	v_pk_mul_f32 v[88:89], v[92:93], v[88:89]
	v_pk_mul_f32 v[90:91], v[94:95], v[90:91]
	v_pk_mul_f32 v[80:81], v[84:85], v[80:81]
	v_pk_mul_f32 v[82:83], v[86:87], v[82:83]
	v_cvt_pk_bf16_f32 v92, v88, v89
	v_cvt_pk_bf16_f32 v93, v90, v91
	v_cvt_pk_bf16_f32 v94, v80, v81
	v_cvt_pk_bf16_f32 v95, v82, v83
	global_store_dwordx4 v147, v[92:95], s[22:23]
	v_fmamk_f32 v244, v244, 0x3a800000, v153
	v_rsq_f32_e32 v244, v244
	v_add_u32_e32 v147, 0x42000, v146
	v_pk_mul_f32 v[72:73], v[72:73], v[244:245] op_sel_hi:[1,0]
	v_pk_mul_f32 v[74:75], v[74:75], v[244:245] op_sel_hi:[1,0]
	v_pk_mul_f32 v[64:65], v[64:65], v[244:245] op_sel_hi:[1,0]
	v_pk_mul_f32 v[66:67], v[66:67], v[244:245] op_sel_hi:[1,0]
	v_pk_mul_f32 v[170:171], v[72:73], v[178:179] op_sel_hi:[1,0]
	v_pk_mul_f32 v[172:173], v[74:75], v[178:179] op_sel_hi:[1,0]
	v_pk_mul_f32 v[174:175], v[64:65], v[178:179] op_sel_hi:[1,0]
	v_pk_mul_f32 v[176:177], v[66:67], v[178:179] op_sel_hi:[1,0]
	v_exp_f32_e32 v170, v170
	v_exp_f32_e32 v171, v171
	v_exp_f32_e32 v172, v172
	v_exp_f32_e32 v173, v173
	v_exp_f32_e32 v174, v174
	v_exp_f32_e32 v175, v175
	v_exp_f32_e32 v176, v176
	v_exp_f32_e32 v177, v177
	v_pk_mul_f32 v[76:77], v[76:77], v[244:245] op_sel_hi:[1,0]
	v_pk_mul_f32 v[78:79], v[78:79], v[244:245] op_sel_hi:[1,0]
	v_pk_mul_f32 v[68:69], v[68:69], v[244:245] op_sel_hi:[1,0]
	v_pk_mul_f32 v[70:71], v[70:71], v[244:245] op_sel_hi:[1,0]
	v_pk_add_f32 v[170:171], v[170:171], v[180:181] op_sel_hi:[1,0]
	v_pk_add_f32 v[172:173], v[172:173], v[180:181] op_sel_hi:[1,0]
	v_pk_add_f32 v[174:175], v[174:175], v[180:181] op_sel_hi:[1,0]
	v_pk_add_f32 v[176:177], v[176:177], v[180:181] op_sel_hi:[1,0]
	v_rcp_f32_e32 v170, v170
	v_rcp_f32_e32 v171, v171
	v_rcp_f32_e32 v172, v172
	v_rcp_f32_e32 v173, v173
	v_rcp_f32_e32 v174, v174
	v_rcp_f32_e32 v175, v175
	v_rcp_f32_e32 v176, v176
	v_rcp_f32_e32 v177, v177
	v_pk_mul_f32 v[72:73], v[72:73], v[170:171]
	v_pk_mul_f32 v[74:75], v[74:75], v[172:173]
	v_pk_mul_f32 v[64:65], v[64:65], v[174:175]
	v_pk_mul_f32 v[66:67], v[66:67], v[176:177]
	v_pk_mul_f32 v[72:73], v[76:77], v[72:73]
	v_pk_mul_f32 v[74:75], v[78:79], v[74:75]
	v_pk_mul_f32 v[64:65], v[68:69], v[64:65]
	v_pk_mul_f32 v[66:67], v[70:71], v[66:67]
	v_cvt_pk_bf16_f32 v76, v72, v73
	v_cvt_pk_bf16_f32 v77, v74, v75
	v_cvt_pk_bf16_f32 v78, v64, v65
	v_cvt_pk_bf16_f32 v79, v66, v67
	global_store_dwordx4 v147, v[76:79], s[22:23]
	v_fmamk_f32 v246, v246, 0x3a800000, v153
	v_rsq_f32_e32 v246, v246
	v_add_u32_e32 v147, 0xb0000, v146
	v_pk_mul_f32 v[56:57], v[56:57], v[246:247] op_sel_hi:[1,0]
	v_pk_mul_f32 v[58:59], v[58:59], v[246:247] op_sel_hi:[1,0]
	v_pk_mul_f32 v[48:49], v[48:49], v[246:247] op_sel_hi:[1,0]
	v_pk_mul_f32 v[50:51], v[50:51], v[246:247] op_sel_hi:[1,0]
	v_pk_mul_f32 v[170:171], v[56:57], v[178:179] op_sel_hi:[1,0]
	v_pk_mul_f32 v[172:173], v[58:59], v[178:179] op_sel_hi:[1,0]
	v_pk_mul_f32 v[174:175], v[48:49], v[178:179] op_sel_hi:[1,0]
	v_pk_mul_f32 v[176:177], v[50:51], v[178:179] op_sel_hi:[1,0]
	v_exp_f32_e32 v170, v170
	v_exp_f32_e32 v171, v171
	v_exp_f32_e32 v172, v172
	v_exp_f32_e32 v173, v173
	v_exp_f32_e32 v174, v174
	v_exp_f32_e32 v175, v175
	v_exp_f32_e32 v176, v176
	v_exp_f32_e32 v177, v177
	v_pk_mul_f32 v[60:61], v[60:61], v[246:247] op_sel_hi:[1,0]
	v_pk_mul_f32 v[62:63], v[62:63], v[246:247] op_sel_hi:[1,0]
	v_pk_mul_f32 v[52:53], v[52:53], v[246:247] op_sel_hi:[1,0]
	v_pk_mul_f32 v[54:55], v[54:55], v[246:247] op_sel_hi:[1,0]
	v_pk_add_f32 v[170:171], v[170:171], v[180:181] op_sel_hi:[1,0]
	v_pk_add_f32 v[172:173], v[172:173], v[180:181] op_sel_hi:[1,0]
	v_pk_add_f32 v[174:175], v[174:175], v[180:181] op_sel_hi:[1,0]
	v_pk_add_f32 v[176:177], v[176:177], v[180:181] op_sel_hi:[1,0]
	v_rcp_f32_e32 v170, v170
	v_rcp_f32_e32 v171, v171
	v_rcp_f32_e32 v172, v172
	v_rcp_f32_e32 v173, v173
	v_rcp_f32_e32 v174, v174
	v_rcp_f32_e32 v175, v175
	v_rcp_f32_e32 v176, v176
	v_rcp_f32_e32 v177, v177
	v_pk_mul_f32 v[56:57], v[56:57], v[170:171]
	v_pk_mul_f32 v[58:59], v[58:59], v[172:173]
	v_pk_mul_f32 v[48:49], v[48:49], v[174:175]
	v_pk_mul_f32 v[50:51], v[50:51], v[176:177]
	v_pk_mul_f32 v[56:57], v[60:61], v[56:57]
	v_pk_mul_f32 v[58:59], v[62:63], v[58:59]
	v_pk_mul_f32 v[48:49], v[52:53], v[48:49]
	v_pk_mul_f32 v[50:51], v[54:55], v[50:51]
	v_cvt_pk_bf16_f32 v60, v56, v57
	v_cvt_pk_bf16_f32 v61, v58, v59
	v_cvt_pk_bf16_f32 v62, v48, v49
	v_cvt_pk_bf16_f32 v63, v50, v51
	global_store_dwordx4 v147, v[60:63], s[22:23]
	v_fmamk_f32 v248, v248, 0x3a800000, v153
	v_rsq_f32_e32 v248, v248
	v_add_u32_e32 v147, 0xc6000, v146
	v_pk_mul_f32 v[40:41], v[40:41], v[248:249] op_sel_hi:[1,0]
	v_pk_mul_f32 v[42:43], v[42:43], v[248:249] op_sel_hi:[1,0]
	v_pk_mul_f32 v[32:33], v[32:33], v[248:249] op_sel_hi:[1,0]
	v_pk_mul_f32 v[34:35], v[34:35], v[248:249] op_sel_hi:[1,0]
	v_pk_mul_f32 v[170:171], v[40:41], v[178:179] op_sel_hi:[1,0]
	v_pk_mul_f32 v[172:173], v[42:43], v[178:179] op_sel_hi:[1,0]
	v_pk_mul_f32 v[174:175], v[32:33], v[178:179] op_sel_hi:[1,0]
; __device__ __forceinline__ u32x4 pack8(f32x4 a, f32x4 b) { u32x4 w; w.x = cvt_pk_bf16(a[0], a[1]); w.y = cvt_pk_bf16(a[2], a[3]); w.z = cvt_pk_bf16(b[0], b[1]); w.w = cvt_pk_bf16(b[2], b[3]); return w; }
; __device__ __forceinline__ float sigm(float x) { return __builtin_amdgcn_rcpf(1.0f + __builtin_amdgcn_exp2f(-x * LOG2E)); }
; __device__ __forceinline__ bf16x8 pack8(const f32x16& p, int b) { u32x4 w; w.x = cvtpk(p[b], p[b + 1]); w.y = cvtpk(p[b + 2], p[b + 3]); w.z = cvtpk(p[b + 4], p[b + 5]); w.w = cvtpk(p[b + 6], p[b + 7]); return __builtin_bit_cast(bf16x8, w); }
;     __device__ __forceinline__ void operator()(const f32x4 (&acc)[2][2][4][2], const Unit& u, int wr, int wc, int fr, int fq) const {
;     ...
;             for (int m = 0; m < 4; ++m) {
;                 const int row = u.pm * BM + ai * HALF + wr * 64 + m * 16 + fr;
;                 const float rs = __builtin_amdgcn_rsqf(ssq[row] * (1.0f / 1024.0f) + EPS);
;                 f32x4 o[2];
; #pragma unroll
;                 for (int n = 0; n < 2; ++n)
; #pragma unroll
;                     for (int i = 0; i < 4; ++i) { const float g = acc[ai][0][m][n][i] * rs, up = acc[ai][1][m][n][i] * rs; o[n][i] = g * sigm(g) * up; }
;                 *(u32x4*)(h + (size_t)row * DFF + u.pn * HALF + wc * 32 + 8 * fq) = pack8(o[0], o[1]);
	v_pk_mul_f32 v[176:177], v[34:35], v[178:179] op_sel_hi:[1,0]
	v_exp_f32_e32 v170, v170
	v_exp_f32_e32 v171, v171
	v_exp_f32_e32 v172, v172
	v_exp_f32_e32 v173, v173
	v_exp_f32_e32 v174, v174
	v_exp_f32_e32 v175, v175
	v_exp_f32_e32 v176, v176
	v_exp_f32_e32 v177, v177
	v_pk_mul_f32 v[44:45], v[44:45], v[248:249] op_sel_hi:[1,0]
	v_pk_mul_f32 v[46:47], v[46:47], v[248:249] op_sel_hi:[1,0]
	v_pk_mul_f32 v[36:37], v[36:37], v[248:249] op_sel_hi:[1,0]
	v_pk_mul_f32 v[38:39], v[38:39], v[248:249] op_sel_hi:[1,0]
	v_pk_add_f32 v[170:171], v[170:171], v[180:181] op_sel_hi:[1,0]
	v_pk_add_f32 v[172:173], v[172:173], v[180:181] op_sel_hi:[1,0]
	v_pk_add_f32 v[174:175], v[174:175], v[180:181] op_sel_hi:[1,0]
	v_pk_add_f32 v[176:177], v[176:177], v[180:181] op_sel_hi:[1,0]
	v_rcp_f32_e32 v170, v170
	v_rcp_f32_e32 v171, v171
	v_rcp_f32_e32 v172, v172
	v_rcp_f32_e32 v173, v173
	v_rcp_f32_e32 v174, v174
	v_rcp_f32_e32 v175, v175
	v_rcp_f32_e32 v176, v176
	v_rcp_f32_e32 v177, v177
	v_pk_mul_f32 v[40:41], v[40:41], v[170:171]
	v_pk_mul_f32 v[42:43], v[42:43], v[172:173]
	v_pk_mul_f32 v[32:33], v[32:33], v[174:175]
	v_pk_mul_f32 v[34:35], v[34:35], v[176:177]
	v_pk_mul_f32 v[40:41], v[44:45], v[40:41]
	v_pk_mul_f32 v[42:43], v[46:47], v[42:43]
	v_pk_mul_f32 v[32:33], v[36:37], v[32:33]
	v_pk_mul_f32 v[34:35], v[38:39], v[34:35]
	v_cvt_pk_bf16_f32 v44, v40, v41
	v_cvt_pk_bf16_f32 v45, v42, v43
	v_cvt_pk_bf16_f32 v46, v32, v33
	v_cvt_pk_bf16_f32 v47, v34, v35
	global_store_dwordx4 v147, v[44:47], s[22:23]
	v_fmamk_f32 v250, v250, 0x3a800000, v153
	v_rsq_f32_e32 v250, v250
	v_add_u32_e32 v147, 0xdc000, v146
	v_pk_mul_f32 v[24:25], v[24:25], v[250:251] op_sel_hi:[1,0]
	v_pk_mul_f32 v[26:27], v[26:27], v[250:251] op_sel_hi:[1,0]
	v_pk_mul_f32 v[16:17], v[16:17], v[250:251] op_sel_hi:[1,0]
	v_pk_mul_f32 v[18:19], v[18:19], v[250:251] op_sel_hi:[1,0]
	v_pk_mul_f32 v[170:171], v[24:25], v[178:179] op_sel_hi:[1,0]
	v_pk_mul_f32 v[172:173], v[26:27], v[178:179] op_sel_hi:[1,0]
	v_pk_mul_f32 v[174:175], v[16:17], v[178:179] op_sel_hi:[1,0]
	v_pk_mul_f32 v[176:177], v[18:19], v[178:179] op_sel_hi:[1,0]
	v_exp_f32_e32 v170, v170
	v_exp_f32_e32 v171, v171
	v_exp_f32_e32 v172, v172
	v_exp_f32_e32 v173, v173
	v_exp_f32_e32 v174, v174
	v_exp_f32_e32 v175, v175
	v_exp_f32_e32 v176, v176
	v_exp_f32_e32 v177, v177
	v_pk_mul_f32 v[28:29], v[28:29], v[250:251] op_sel_hi:[1,0]
	v_pk_mul_f32 v[30:31], v[30:31], v[250:251] op_sel_hi:[1,0]
	v_pk_mul_f32 v[20:21], v[20:21], v[250:251] op_sel_hi:[1,0]
	v_pk_mul_f32 v[22:23], v[22:23], v[250:251] op_sel_hi:[1,0]
	v_pk_add_f32 v[170:171], v[170:171], v[180:181] op_sel_hi:[1,0]
	v_pk_add_f32 v[172:173], v[172:173], v[180:181] op_sel_hi:[1,0]
	v_pk_add_f32 v[174:175], v[174:175], v[180:181] op_sel_hi:[1,0]
	v_pk_add_f32 v[176:177], v[176:177], v[180:181] op_sel_hi:[1,0]
	v_rcp_f32_e32 v170, v170
	v_rcp_f32_e32 v171, v171
	v_rcp_f32_e32 v172, v172
	v_rcp_f32_e32 v173, v173
	v_rcp_f32_e32 v174, v174
	v_rcp_f32_e32 v175, v175
	v_rcp_f32_e32 v176, v176
	v_rcp_f32_e32 v177, v177
	v_pk_mul_f32 v[24:25], v[24:25], v[170:171]
	v_pk_mul_f32 v[26:27], v[26:27], v[172:173]
	v_pk_mul_f32 v[16:17], v[16:17], v[174:175]
	v_pk_mul_f32 v[18:19], v[18:19], v[176:177]
	v_pk_mul_f32 v[24:25], v[28:29], v[24:25]
	v_pk_mul_f32 v[26:27], v[30:31], v[26:27]
	v_pk_mul_f32 v[16:17], v[20:21], v[16:17]
	v_pk_mul_f32 v[18:19], v[22:23], v[18:19]
	v_cvt_pk_bf16_f32 v28, v24, v25
	v_cvt_pk_bf16_f32 v29, v26, v27
	v_cvt_pk_bf16_f32 v30, v16, v17
	v_cvt_pk_bf16_f32 v31, v18, v19
	global_store_dwordx4 v147, v[28:31], s[22:23]
	v_fmamk_f32 v252, v252, 0x3a800000, v153
	v_rsq_f32_e32 v252, v252
	v_add_u32_e32 v147, 0xf2000, v146
	v_pk_mul_f32 v[8:9], v[8:9], v[252:253] op_sel_hi:[1,0]
	v_pk_mul_f32 v[10:11], v[10:11], v[252:253] op_sel_hi:[1,0]
	v_pk_mul_f32 v[0:1], v[0:1], v[252:253] op_sel_hi:[1,0]
	v_pk_mul_f32 v[2:3], v[2:3], v[252:253] op_sel_hi:[1,0]
	v_pk_mul_f32 v[170:171], v[8:9], v[178:179] op_sel_hi:[1,0]
	v_pk_mul_f32 v[172:173], v[10:11], v[178:179] op_sel_hi:[1,0]
	v_pk_mul_f32 v[174:175], v[0:1], v[178:179] op_sel_hi:[1,0]
	v_pk_mul_f32 v[176:177], v[2:3], v[178:179] op_sel_hi:[1,0]
	v_exp_f32_e32 v170, v170
	v_exp_f32_e32 v171, v171
	v_exp_f32_e32 v172, v172
	v_exp_f32_e32 v173, v173
	v_exp_f32_e32 v174, v174
	v_exp_f32_e32 v175, v175
	v_exp_f32_e32 v176, v176
	v_exp_f32_e32 v177, v177
	v_pk_mul_f32 v[12:13], v[12:13], v[252:253] op_sel_hi:[1,0]
	v_pk_mul_f32 v[14:15], v[14:15], v[252:253] op_sel_hi:[1,0]
	v_pk_mul_f32 v[4:5], v[4:5], v[252:253] op_sel_hi:[1,0]
	v_pk_mul_f32 v[6:7], v[6:7], v[252:253] op_sel_hi:[1,0]
	v_pk_add_f32 v[170:171], v[170:171], v[180:181] op_sel_hi:[1,0]
	v_pk_add_f32 v[172:173], v[172:173], v[180:181] op_sel_hi:[1,0]
	v_pk_add_f32 v[174:175], v[174:175], v[180:181] op_sel_hi:[1,0]
	v_pk_add_f32 v[176:177], v[176:177], v[180:181] op_sel_hi:[1,0]
	v_rcp_f32_e32 v170, v170
	v_rcp_f32_e32 v171, v171
	v_rcp_f32_e32 v172, v172
	v_rcp_f32_e32 v173, v173
	v_rcp_f32_e32 v174, v174
	v_rcp_f32_e32 v175, v175
	v_rcp_f32_e32 v176, v176
	v_rcp_f32_e32 v177, v177
	v_pk_mul_f32 v[8:9], v[8:9], v[170:171]
	v_pk_mul_f32 v[10:11], v[10:11], v[172:173]
	v_pk_mul_f32 v[0:1], v[0:1], v[174:175]
	v_pk_mul_f32 v[2:3], v[2:3], v[176:177]
	v_pk_mul_f32 v[8:9], v[12:13], v[8:9]
	v_pk_mul_f32 v[10:11], v[14:15], v[10:11]
	v_pk_mul_f32 v[0:1], v[4:5], v[0:1]
	v_pk_mul_f32 v[2:3], v[6:7], v[2:3]
	v_cvt_pk_bf16_f32 v12, v8, v9
	v_cvt_pk_bf16_f32 v13, v10, v11
	v_cvt_pk_bf16_f32 v14, v0, v1
	v_cvt_pk_bf16_f32 v15, v2, v3
	global_store_dwordx4 v147, v[12:15], s[22:23]
	s_cbranch_vccnz .LBB0_1162
	s_andn2_b64 vcc, exec, s[10:11]
	s_cbranch_vccnz .LBB0_1161
	s_barrier
	s_branch .LBB0_1161
